# v108 plus SwiGLU epilogue overlap: last K-loop iteration peeled, epilogue block 0 and half of block 1 interleaved between the MFMA pairs of the final interval
# baseline (speedup 1.0000x reference)
; #define PG8_STAGE(bufoff, gbase, voff) do { _Pragma("unroll") for (int _i = 0; _i < 2; ++_i) \
;         __builtin_amdgcn_global_load_lds((const unsigned*)((const char*)(gbase) + (voff)[_i]), (PG8_LAS unsigned*)(lds + (bufoff) + ldsw + _i * 8192), 16, 0, 0); } while (0)
; #define PG8_LDA(dst, b, h) do { _Pragma("unroll") for (int m = 0; m < 4; ++m) _Pragma("unroll") for (int k = 0; k < 2; ++k) dst[m][k] = *(const PG8_LAS bf16x8*)(lds + PG8_SA(b, h) + aoff + m * 2048 + k * 1024); } while (0)
; #define PG8_LDB(dst, b, h) do { _Pragma("unroll") for (int n = 0; n < 2; ++n) _Pragma("unroll") for (int k = 0; k < 2; ++k) dst[n][k] = *(const PG8_LAS bf16x8*)(lds + PG8_SB(b, h) + boff + n * 2048 + k * 1024); } while (0)
; #define PG8_MMA(ai, bj, At, Bt) do { __builtin_amdgcn_s_setprio(1); _Pragma("unroll") for (int m = 0; m < 4; ++m) _Pragma("unroll") for (int n = 0; n < 2; ++n) _Pragma("unroll") for (int k = 0; k < 2; ++k) \
;         acc[ai][bj][m][n] = __builtin_amdgcn_mfma_f32_16x16x32_bf16(Bt[n][k], At[m][k], acc[ai][bj][m][n], 0, 0, 0); __builtin_amdgcn_s_setprio(0); } while (0)
; #define PG8_WAIT_V(n) asm volatile("s_waitcnt vmcnt(" #n ")" ::: "memory")
; template <class Epi, class Sched, bool ALIGN_EPI = false, bool SP2 = false>
; __device__ __forceinline__ void gemm_phase(PG8_LAS unsigned char* lds, const Gemm g, const Sched& S, const Epi& E) {
;     ...
;             PG8_LDB(B0, 0, 0); PG8_LDB(B1, 0, 1); PG8_SCHED; PG8_LDA(At, 0, 0); PG8_STAGE(PG8_SA(1, 1), a1 + hstep, voffA);
;             PG8_WAIT_V(8); PG8_WAIT_L(0); PG8_BAR; PG8_MMA(0, 0, At, B0); PG8_MMA(0, 1, At, B1); PG8_BAR; PG8_SCHED;
;             PG8_LDA(At, 0, 1); PG8_STAGE(PG8_SB(0, 0), b2, voffB); PG8_STAGE(PG8_SB(0, 1), b2 + hstep, voffB); PG8_STAGE(PG8_SA(0, 0), a2, voffA);
;             PG8_WAIT_V(8); PG8_WAIT_L(0); PG8_BAR; PG8_MMA(1, 0, At, B0); PG8_MMA(1, 1, At, B1); PG8_BAR; PG8_SCHED;
;             PG8_LDB(B0, 1, 0); PG8_LDB(B1, 1, 1); PG8_SCHED; PG8_LDA(At, 1, 0); PG8_STAGE(PG8_SA(0, 1), a2 + hstep, voffA);
;             PG8_WAIT_V(8); PG8_WAIT_L(0); PG8_BAR; PG8_MMA(0, 0, At, B0); PG8_MMA(0, 1, At, B1); PG8_BAR; PG8_SCHED;
;             PG8_LDA(At, 1, 1); PG8_STAGE(PG8_SB(1, 0), b3, voffB); PG8_STAGE(PG8_SB(1, 1), b3 + hstep, voffB); PG8_STAGE(PG8_SA(1, 0), a3, voffA);
;             PG8_WAIT_V(8); PG8_WAIT_L(0); PG8_BAR; PG8_MMA(1, 0, At, B0); PG8_MMA(1, 1, At, B1); PG8_BAR; PG8_SCHED;
.LBB0_102:
	ds_read_b128 v[160:163], v155
	ds_read_b128 v[164:167], v155 offset:1024
	ds_read_b128 v[168:171], v155 offset:2048
	ds_read_b128 v[172:175], v155 offset:3072
	ds_read_b128 v[176:179], v157
	ds_read_b128 v[180:183], v157 offset:1024
	ds_read_b128 v[184:187], v157 offset:2048
	ds_read_b128 v[188:191], v157 offset:3072
	s_add_u32 s62, s74, 0xfff80080
	s_addc_u32 s63, s75, -1
	s_cmp_eq_u32 s90, 28
	s_cselect_b32 s79, s10, s63
	s_cselect_b32 s78, s11, s62
	s_cselect_b32 s77, s51, s89
	s_cselect_b32 s76, s55, s88
	v_lshl_add_u64 v[224:225], s[74:75], 0, v[138:139]
	s_add_i32 m0, s61, 0xc000
	ds_read_b128 v[192:195], v159
	ds_read_b128 v[196:199], v159 offset:1024
	ds_read_b128 v[200:203], v159 offset:2048
	ds_read_b128 v[204:207], v159 offset:3072
	ds_read_b128 v[208:211], v159 offset:4096
	ds_read_b128 v[212:215], v159 offset:5120
	ds_read_b128 v[216:219], v159 offset:6144
	ds_read_b128 v[220:223], v159 offset:7168
	global_load_lds_dwordx4 v[224:225], off
	v_lshl_add_u64 v[224:225], s[74:75], 0, v[140:141]
	s_add_i32 m0, s61, 0xe000
	s_nop 0
	global_load_lds_dwordx4 v[224:225], off
	s_waitcnt vmcnt(8)
	s_waitcnt lgkmcnt(0)
	s_setprio 1
	s_barrier
	v_mfma_f32_16x16x32_bf16 v[124:127], v[160:163], v[192:195], v[124:127]
	v_mfma_f32_16x16x32_bf16 v[124:127], v[164:167], v[196:199], v[124:127]
	v_mfma_f32_16x16x32_bf16 v[108:111], v[160:163], v[200:203], v[108:111]
	v_mfma_f32_16x16x32_bf16 v[108:111], v[164:167], v[204:207], v[108:111]
	v_mfma_f32_16x16x32_bf16 v[92:95], v[160:163], v[208:211], v[92:95]
	v_mfma_f32_16x16x32_bf16 v[92:95], v[164:167], v[212:215], v[92:95]
	v_mfma_f32_16x16x32_bf16 v[76:79], v[160:163], v[216:219], v[76:79]
	v_mfma_f32_16x16x32_bf16 v[76:79], v[164:167], v[220:223], v[76:79]
	v_mfma_f32_16x16x32_bf16 v[72:75], v[168:171], v[216:219], v[72:75]
	v_mfma_f32_16x16x32_bf16 v[72:75], v[172:175], v[220:223], v[72:75]
	v_mfma_f32_16x16x32_bf16 v[88:91], v[168:171], v[208:211], v[88:91]
	v_mfma_f32_16x16x32_bf16 v[88:91], v[172:175], v[212:215], v[88:91]
	v_mfma_f32_16x16x32_bf16 v[104:107], v[168:171], v[200:203], v[104:107]
	v_mfma_f32_16x16x32_bf16 v[104:107], v[172:175], v[204:207], v[104:107]
	v_mfma_f32_16x16x32_bf16 v[120:123], v[168:171], v[192:195], v[120:123]
	v_mfma_f32_16x16x32_bf16 v[120:123], v[172:175], v[196:199], v[120:123]
	v_mfma_f32_16x16x32_bf16 v[116:119], v[176:179], v[192:195], v[116:119]
	v_mfma_f32_16x16x32_bf16 v[116:119], v[180:183], v[196:199], v[116:119]
	v_mfma_f32_16x16x32_bf16 v[100:103], v[176:179], v[200:203], v[100:103]
	v_mfma_f32_16x16x32_bf16 v[100:103], v[180:183], v[204:207], v[100:103]
	v_mfma_f32_16x16x32_bf16 v[84:87], v[176:179], v[208:211], v[84:87]
	v_mfma_f32_16x16x32_bf16 v[84:87], v[180:183], v[212:215], v[84:87]
	v_mfma_f32_16x16x32_bf16 v[68:71], v[176:179], v[216:219], v[68:71]
	v_mfma_f32_16x16x32_bf16 v[68:71], v[180:183], v[220:223], v[68:71]
	v_mfma_f32_16x16x32_bf16 v[64:67], v[184:187], v[216:219], v[64:67]
	v_mfma_f32_16x16x32_bf16 v[64:67], v[188:191], v[220:223], v[64:67]
	v_mfma_f32_16x16x32_bf16 v[80:83], v[184:187], v[208:211], v[80:83]
	v_mfma_f32_16x16x32_bf16 v[80:83], v[188:191], v[212:215], v[80:83]
	s_setprio 2
	s_barrier
	v_mfma_f32_16x16x32_bf16 v[96:99], v[184:187], v[200:203], v[96:99]
	v_mfma_f32_16x16x32_bf16 v[96:99], v[188:191], v[204:207], v[96:99]
	v_mfma_f32_16x16x32_bf16 v[112:115], v[184:187], v[192:195], v[112:115]
	v_mfma_f32_16x16x32_bf16 v[112:115], v[188:191], v[196:199], v[112:115]
	s_setprio 0
	s_add_i32 s62, s84, s35
	v_lshl_add_u64 v[224:225], s[76:77], 0, v[130:131]
	s_mov_b32 m0, s62
	ds_read_b128 v[192:195], v159 offset:16384
	ds_read_b128 v[196:199], v159 offset:17408
	ds_read_b128 v[200:203], v159 offset:18432
	ds_read_b128 v[204:207], v159 offset:19456
	ds_read_b128 v[208:211], v159 offset:20480
	ds_read_b128 v[212:215], v159 offset:21504
	ds_read_b128 v[216:219], v159 offset:22528
	ds_read_b128 v[220:223], v159 offset:23552
	global_load_lds_dwordx4 v[224:225], off
	s_add_i32 m0, s62, 0x2000
	s_add_u32 s92, s76, 0x80000
	v_lshl_add_u64 v[226:227], s[76:77], 0, v[134:135]
	s_addc_u32 s93, s77, 0
	s_add_i32 s62, s85, s35
	global_load_lds_dwordx4 v[226:227], off
	v_lshl_add_u64 v[228:229], s[92:93], 0, v[130:131]
	s_mov_b32 m0, s62
	v_lshl_add_u64 v[230:231], s[78:79], 0, v[132:133]
	global_load_lds_dwordx4 v[228:229], off
	v_lshl_add_u64 v[228:229], s[92:93], 0, v[134:135]
	s_add_i32 m0, s62, 0x2000
	s_nop 0
	global_load_lds_dwordx4 v[228:229], off
	v_lshl_add_u64 v[228:229], s[78:79], 0, v[128:129]
	s_mov_b32 m0, s61
	s_nop 0
	global_load_lds_dwordx4 v[228:229], off
	s_mov_b32 m0, s65
	s_nop 0
	global_load_lds_dwordx4 v[230:231], off
	s_waitcnt vmcnt(8)
	s_waitcnt lgkmcnt(0)
	s_setprio 1
	s_barrier
; #define PG8_STAGE(bufoff, gbase, voff) do { _Pragma("unroll") for (int _i = 0; _i < 2; ++_i) \
;         __builtin_amdgcn_global_load_lds((const unsigned*)((const char*)(gbase) + (voff)[_i]), (PG8_LAS unsigned*)(lds + (bufoff) + ldsw + _i * 8192), 16, 0, 0); } while (0)
; #define PG8_LDA(dst, b, h) do { _Pragma("unroll") for (int m = 0; m < 4; ++m) _Pragma("unroll") for (int k = 0; k < 2; ++k) dst[m][k] = *(const PG8_LAS bf16x8*)(lds + PG8_SA(b, h) + aoff + m * 2048 + k * 1024); } while (0)
; #define PG8_LDB(dst, b, h) do { _Pragma("unroll") for (int n = 0; n < 2; ++n) _Pragma("unroll") for (int k = 0; k < 2; ++k) dst[n][k] = *(const PG8_LAS bf16x8*)(lds + PG8_SB(b, h) + boff + n * 2048 + k * 1024); } while (0)
; #define PG8_MMA(ai, bj, At, Bt) do { __builtin_amdgcn_s_setprio(1); _Pragma("unroll") for (int m = 0; m < 4; ++m) _Pragma("unroll") for (int n = 0; n < 2; ++n) _Pragma("unroll") for (int k = 0; k < 2; ++k) \
;         acc[ai][bj][m][n] = __builtin_amdgcn_mfma_f32_16x16x32_bf16(Bt[n][k], At[m][k], acc[ai][bj][m][n], 0, 0, 0); __builtin_amdgcn_s_setprio(0); } while (0)
; #define PG8_WAIT_V(n) asm volatile("s_waitcnt vmcnt(" #n ")" ::: "memory")
; template <class Epi, class Sched, bool ALIGN_EPI = false, bool SP2 = false>
; __device__ __forceinline__ void gemm_phase(PG8_LAS unsigned char* lds, const Gemm g, const Sched& S, const Epi& E) {
;     ...
;             PG8_LDB(B0, 0, 0); PG8_LDB(B1, 0, 1); PG8_SCHED; PG8_LDA(At, 0, 0); PG8_STAGE(PG8_SA(1, 1), a1 + hstep, voffA);
;             PG8_WAIT_V(8); PG8_WAIT_L(0); PG8_BAR; PG8_MMA(0, 0, At, B0); PG8_MMA(0, 1, At, B1); PG8_BAR; PG8_SCHED;
;             PG8_LDA(At, 0, 1); PG8_STAGE(PG8_SB(0, 0), b2, voffB); PG8_STAGE(PG8_SB(0, 1), b2 + hstep, voffB); PG8_STAGE(PG8_SA(0, 0), a2, voffA);
;             PG8_WAIT_V(8); PG8_WAIT_L(0); PG8_BAR; PG8_MMA(1, 0, At, B0); PG8_MMA(1, 1, At, B1); PG8_BAR; PG8_SCHED;
;             PG8_LDB(B0, 1, 0); PG8_LDB(B1, 1, 1); PG8_SCHED; PG8_LDA(At, 1, 0); PG8_STAGE(PG8_SA(0, 1), a2 + hstep, voffA);
;             PG8_WAIT_V(8); PG8_WAIT_L(0); PG8_BAR; PG8_MMA(0, 0, At, B0); PG8_MMA(0, 1, At, B1); PG8_BAR; PG8_SCHED;
;             PG8_LDA(At, 1, 1); PG8_STAGE(PG8_SB(1, 0), b3, voffB); PG8_STAGE(PG8_SB(1, 1), b3 + hstep, voffB); PG8_STAGE(PG8_SA(1, 0), a3, voffA);
;             PG8_WAIT_V(8); PG8_WAIT_L(0); PG8_BAR; PG8_MMA(1, 0, At, B0); PG8_MMA(1, 1, At, B1); PG8_BAR; PG8_SCHED;
	v_mfma_f32_16x16x32_bf16 v[60:63], v[160:163], v[192:195], v[60:63]
	v_mfma_f32_16x16x32_bf16 v[60:63], v[164:167], v[196:199], v[60:63]
	v_mfma_f32_16x16x32_bf16 v[44:47], v[160:163], v[200:203], v[44:47]
	v_mfma_f32_16x16x32_bf16 v[44:47], v[164:167], v[204:207], v[44:47]
	v_mfma_f32_16x16x32_bf16 v[28:31], v[160:163], v[208:211], v[28:31]
	v_mfma_f32_16x16x32_bf16 v[28:31], v[164:167], v[212:215], v[28:31]
	v_mfma_f32_16x16x32_bf16 v[12:15], v[160:163], v[216:219], v[12:15]
	v_mfma_f32_16x16x32_bf16 v[12:15], v[164:167], v[220:223], v[12:15]
	v_mfma_f32_16x16x32_bf16 v[8:11], v[168:171], v[216:219], v[8:11]
	v_mfma_f32_16x16x32_bf16 v[8:11], v[172:175], v[220:223], v[8:11]
	v_mfma_f32_16x16x32_bf16 v[24:27], v[168:171], v[208:211], v[24:27]
	v_mfma_f32_16x16x32_bf16 v[24:27], v[172:175], v[212:215], v[24:27]
	v_mfma_f32_16x16x32_bf16 v[40:43], v[168:171], v[200:203], v[40:43]
	v_mfma_f32_16x16x32_bf16 v[40:43], v[172:175], v[204:207], v[40:43]
	v_mfma_f32_16x16x32_bf16 v[56:59], v[168:171], v[192:195], v[56:59]
	v_mfma_f32_16x16x32_bf16 v[56:59], v[172:175], v[196:199], v[56:59]
	v_mfma_f32_16x16x32_bf16 v[52:55], v[176:179], v[192:195], v[52:55]
	v_mfma_f32_16x16x32_bf16 v[52:55], v[180:183], v[196:199], v[52:55]
	v_mfma_f32_16x16x32_bf16 v[36:39], v[176:179], v[200:203], v[36:39]
	v_mfma_f32_16x16x32_bf16 v[36:39], v[180:183], v[204:207], v[36:39]
	v_mfma_f32_16x16x32_bf16 v[20:23], v[176:179], v[208:211], v[20:23]
	v_mfma_f32_16x16x32_bf16 v[20:23], v[180:183], v[212:215], v[20:23]
	v_mfma_f32_16x16x32_bf16 v[4:7], v[176:179], v[216:219], v[4:7]
	v_mfma_f32_16x16x32_bf16 v[4:7], v[180:183], v[220:223], v[4:7]
	v_mfma_f32_16x16x32_bf16 v[0:3], v[184:187], v[216:219], v[0:3]
	v_mfma_f32_16x16x32_bf16 v[0:3], v[188:191], v[220:223], v[0:3]
	v_mfma_f32_16x16x32_bf16 v[16:19], v[184:187], v[208:211], v[16:19]
	v_mfma_f32_16x16x32_bf16 v[16:19], v[188:191], v[212:215], v[16:19]
	s_setprio 2
	s_barrier
	v_mfma_f32_16x16x32_bf16 v[32:35], v[184:187], v[200:203], v[32:35]
	v_mfma_f32_16x16x32_bf16 v[32:35], v[188:191], v[204:207], v[32:35]
	v_mfma_f32_16x16x32_bf16 v[48:51], v[184:187], v[192:195], v[48:51]
	v_mfma_f32_16x16x32_bf16 v[48:51], v[188:191], v[196:199], v[48:51]
	s_setprio 0
	s_add_i32 s62, 0, 0x18000
	s_add_i32 s63, 0, 0x1c000
	v_add_u32_e32 v172, s62, v147
	v_add_u32_e32 v188, s63, v147
	ds_read_b128 v[160:163], v172
	ds_read_b128 v[164:167], v172 offset:1024
	ds_read_b128 v[168:171], v172 offset:2048
	ds_read_b128 v[172:175], v172 offset:3072
	ds_read_b128 v[176:179], v188
	ds_read_b128 v[180:183], v188 offset:1024
	ds_read_b128 v[184:187], v188 offset:2048
	ds_read_b128 v[188:191], v188 offset:3072
	s_add_u32 s78, s78, 0x80000
	s_addc_u32 s79, s79, 0
	s_mov_b32 m0, s66
	v_lshl_add_u64 v[232:233], s[78:79], 0, v[128:129]
	ds_read_b128 v[192:195], v159 offset:32768
	ds_read_b128 v[196:199], v159 offset:33792
	ds_read_b128 v[200:203], v159 offset:34816
	ds_read_b128 v[204:207], v159 offset:35840
	ds_read_b128 v[208:211], v159 offset:36864
	ds_read_b128 v[212:215], v159 offset:37888
	ds_read_b128 v[216:219], v159 offset:38912
	ds_read_b128 v[220:223], v159 offset:39936
	global_load_lds_dwordx4 v[232:233], off
	v_lshl_add_u64 v[232:233], s[78:79], 0, v[132:133]
	s_mov_b32 m0, s67
	s_nop 0
	global_load_lds_dwordx4 v[232:233], off
	s_waitcnt vmcnt(8)
	s_waitcnt lgkmcnt(0)
	s_setprio 1
	s_barrier
	v_mfma_f32_16x16x32_bf16 v[124:127], v[160:163], v[192:195], v[124:127]
	v_mfma_f32_16x16x32_bf16 v[124:127], v[164:167], v[196:199], v[124:127]
	v_mfma_f32_16x16x32_bf16 v[108:111], v[160:163], v[200:203], v[108:111]
	v_mfma_f32_16x16x32_bf16 v[108:111], v[164:167], v[204:207], v[108:111]
	v_mfma_f32_16x16x32_bf16 v[92:95], v[160:163], v[208:211], v[92:95]
	v_mfma_f32_16x16x32_bf16 v[92:95], v[164:167], v[212:215], v[92:95]
	v_mfma_f32_16x16x32_bf16 v[76:79], v[160:163], v[216:219], v[76:79]
	v_mfma_f32_16x16x32_bf16 v[76:79], v[164:167], v[220:223], v[76:79]
	v_mfma_f32_16x16x32_bf16 v[72:75], v[168:171], v[216:219], v[72:75]
	v_mfma_f32_16x16x32_bf16 v[72:75], v[172:175], v[220:223], v[72:75]
	v_mfma_f32_16x16x32_bf16 v[88:91], v[168:171], v[208:211], v[88:91]
	v_mfma_f32_16x16x32_bf16 v[88:91], v[172:175], v[212:215], v[88:91]
	v_mfma_f32_16x16x32_bf16 v[104:107], v[168:171], v[200:203], v[104:107]
	v_mfma_f32_16x16x32_bf16 v[104:107], v[172:175], v[204:207], v[104:107]
	v_mfma_f32_16x16x32_bf16 v[120:123], v[168:171], v[192:195], v[120:123]
	v_mfma_f32_16x16x32_bf16 v[120:123], v[172:175], v[196:199], v[120:123]
	v_mfma_f32_16x16x32_bf16 v[116:119], v[176:179], v[192:195], v[116:119]
	v_mfma_f32_16x16x32_bf16 v[116:119], v[180:183], v[196:199], v[116:119]
	v_mfma_f32_16x16x32_bf16 v[100:103], v[176:179], v[200:203], v[100:103]
	v_mfma_f32_16x16x32_bf16 v[100:103], v[180:183], v[204:207], v[100:103]
	v_mfma_f32_16x16x32_bf16 v[84:87], v[176:179], v[208:211], v[84:87]
	v_mfma_f32_16x16x32_bf16 v[84:87], v[180:183], v[212:215], v[84:87]
	v_mfma_f32_16x16x32_bf16 v[68:71], v[176:179], v[216:219], v[68:71]
	v_mfma_f32_16x16x32_bf16 v[68:71], v[180:183], v[220:223], v[68:71]
	v_mfma_f32_16x16x32_bf16 v[64:67], v[184:187], v[216:219], v[64:67]
	v_mfma_f32_16x16x32_bf16 v[64:67], v[188:191], v[220:223], v[64:67]
	v_mfma_f32_16x16x32_bf16 v[80:83], v[184:187], v[208:211], v[80:83]
	v_mfma_f32_16x16x32_bf16 v[80:83], v[188:191], v[212:215], v[80:83]
	s_setprio 2
	s_barrier
; #define PG8_STAGE(bufoff, gbase, voff) do { _Pragma("unroll") for (int _i = 0; _i < 2; ++_i) \
;         __builtin_amdgcn_global_load_lds((const unsigned*)((const char*)(gbase) + (voff)[_i]), (PG8_LAS unsigned*)(lds + (bufoff) + ldsw + _i * 8192), 16, 0, 0); } while (0)
; #define PG8_LDA(dst, b, h) do { _Pragma("unroll") for (int m = 0; m < 4; ++m) _Pragma("unroll") for (int k = 0; k < 2; ++k) dst[m][k] = *(const PG8_LAS bf16x8*)(lds + PG8_SA(b, h) + aoff + m * 2048 + k * 1024); } while (0)
; #define PG8_LDB(dst, b, h) do { _Pragma("unroll") for (int n = 0; n < 2; ++n) _Pragma("unroll") for (int k = 0; k < 2; ++k) dst[n][k] = *(const PG8_LAS bf16x8*)(lds + PG8_SB(b, h) + boff + n * 2048 + k * 1024); } while (0)
; #define PG8_WAIT_V(n) asm volatile("s_waitcnt vmcnt(" #n ")" ::: "memory")
; #define PG8_WAIT_L(n) asm volatile("s_waitcnt lgkmcnt(" #n ")" ::: "memory")
; #define PG8_BAR __builtin_amdgcn_s_barrier()
; #define PG8_SCHED __builtin_amdgcn_sched_barrier(0)
; template <class Epi, class Sched, bool ALIGN_EPI = false, bool SP2 = false>
; __device__ __forceinline__ void gemm_phase(PG8_LAS unsigned char* lds, const Gemm g, const Sched& S, const Epi& E) {
;     ...
;         for (int t = 0; t < nt; t += 2) {
;             const bool last = (t == nt - 2);
;             const char* a1 = cA + (size_t)(t + 1) * kstep;
;             const char* a2 = last ? nA : cA + (size_t)(t + 2) * kstep; const char* b2 = last ? nB : cB + (size_t)(t + 2) * kstep;
;             const char* a3 = a2 + kstep; const char* b3 = b2 + kstep;
;             if (last && has_next) S.a_ready(nxt);
;             if constexpr (SP2) {
;             PG8_LDB(B0, 0, 0); PG8_LDB(B1, 0, 1); PG8_SCHED; PG8_LDA(At, 0, 0); PG8_STAGE(PG8_SA(1, 1), a1 + hstep, voffA);
;             PG8_WAIT_V(8); PG8_WAIT_L(0); PG8_BAR; PG8_MMA(0, 0, At, B0); PG8_MMA(0, 1, At, B1); PG8_BAR; PG8_SCHED;
;     ...
;             PG8_LDB(B0, 1, 0); PG8_LDB(B1, 1, 1); PG8_SCHED; PG8_LDA(At, 1, 0); PG8_STAGE(PG8_SA(0, 1), a2 + hstep, voffA);
;             PG8_WAIT_V(8); PG8_WAIT_L(0); PG8_BAR; PG8_MMA(0, 0, At, B0); PG8_MMA(0, 1, At, B1); PG8_BAR; PG8_SCHED;
;             PG8_LDA(At, 1, 1); PG8_STAGE(PG8_SB(1, 0), b3, voffB); PG8_STAGE(PG8_SB(1, 1), b3 + hstep, voffB); PG8_STAGE(PG8_SA(1, 0), a3, voffA);
;             PG8_WAIT_V(8); PG8_WAIT_L(0); PG8_BAR; PG8_MMA(1, 0, At, B0); PG8_MMA(1, 1, At, B1); PG8_BAR; PG8_SCHED;
	v_mfma_f32_16x16x32_bf16 v[96:99], v[184:187], v[200:203], v[96:99]
	v_mfma_f32_16x16x32_bf16 v[96:99], v[188:191], v[204:207], v[96:99]
	v_mfma_f32_16x16x32_bf16 v[112:115], v[184:187], v[192:195], v[112:115]
	v_mfma_f32_16x16x32_bf16 v[112:115], v[188:191], v[196:199], v[112:115]
	s_setprio 0
	s_add_i32 s62, s62, s35
	v_lshl_add_u64 v[224:225], v[224:225], 0, s[18:19]
	s_mov_b32 m0, s62
	ds_read_b128 v[192:195], v159 offset:49152
	ds_read_b128 v[196:199], v159 offset:50176
	ds_read_b128 v[200:203], v159 offset:51200
	ds_read_b128 v[204:207], v159 offset:52224
	ds_read_b128 v[208:211], v159 offset:53248
	ds_read_b128 v[212:215], v159 offset:54272
	ds_read_b128 v[216:219], v159 offset:55296
	ds_read_b128 v[220:223], v159 offset:56320
	global_load_lds_dwordx4 v[224:225], off
	s_add_i32 m0, s62, 0x2000
	s_add_u32 s76, s76, 0x80080
	v_lshl_add_u64 v[224:225], v[226:227], 0, s[18:19]
	s_addc_u32 s77, s77, 0
	s_add_i32 s62, s63, s35
	global_load_lds_dwordx4 v[224:225], off
	v_lshl_add_u64 v[224:225], s[76:77], 0, v[130:131]
	s_mov_b32 m0, s62
	s_nop 0
	global_load_lds_dwordx4 v[224:225], off
	v_lshl_add_u64 v[224:225], s[76:77], 0, v[134:135]
	s_add_i32 m0, s62, 0x2000
	s_nop 0
	global_load_lds_dwordx4 v[224:225], off
	v_lshl_add_u64 v[224:225], v[228:229], 0, s[18:19]
	s_mov_b32 m0, s81
	s_nop 0
	global_load_lds_dwordx4 v[224:225], off
	v_lshl_add_u64 v[224:225], v[230:231], 0, s[18:19]
	s_mov_b32 m0, s82
	s_nop 0
	global_load_lds_dwordx4 v[224:225], off
	s_waitcnt vmcnt(8)
	s_waitcnt lgkmcnt(0)
	s_setprio 1
	s_barrier
	v_mfma_f32_16x16x32_bf16 v[60:63], v[160:163], v[192:195], v[60:63]
	v_mfma_f32_16x16x32_bf16 v[60:63], v[164:167], v[196:199], v[60:63]
	v_mfma_f32_16x16x32_bf16 v[44:47], v[160:163], v[200:203], v[44:47]
	v_mfma_f32_16x16x32_bf16 v[44:47], v[164:167], v[204:207], v[44:47]
	v_mfma_f32_16x16x32_bf16 v[28:31], v[160:163], v[208:211], v[28:31]
	v_mfma_f32_16x16x32_bf16 v[28:31], v[164:167], v[212:215], v[28:31]
	v_mfma_f32_16x16x32_bf16 v[12:15], v[160:163], v[216:219], v[12:15]
	v_mfma_f32_16x16x32_bf16 v[12:15], v[164:167], v[220:223], v[12:15]
	v_mfma_f32_16x16x32_bf16 v[8:11], v[168:171], v[216:219], v[8:11]
	v_mfma_f32_16x16x32_bf16 v[8:11], v[172:175], v[220:223], v[8:11]
	v_mfma_f32_16x16x32_bf16 v[24:27], v[168:171], v[208:211], v[24:27]
	v_mfma_f32_16x16x32_bf16 v[24:27], v[172:175], v[212:215], v[24:27]
	v_mfma_f32_16x16x32_bf16 v[40:43], v[168:171], v[200:203], v[40:43]
	v_mfma_f32_16x16x32_bf16 v[40:43], v[172:175], v[204:207], v[40:43]
	v_mfma_f32_16x16x32_bf16 v[56:59], v[168:171], v[192:195], v[56:59]
	v_mfma_f32_16x16x32_bf16 v[56:59], v[172:175], v[196:199], v[56:59]
	v_mfma_f32_16x16x32_bf16 v[52:55], v[176:179], v[192:195], v[52:55]
	v_mfma_f32_16x16x32_bf16 v[52:55], v[180:183], v[196:199], v[52:55]
	v_mfma_f32_16x16x32_bf16 v[36:39], v[176:179], v[200:203], v[36:39]
	v_mfma_f32_16x16x32_bf16 v[36:39], v[180:183], v[204:207], v[36:39]
	v_mfma_f32_16x16x32_bf16 v[20:23], v[176:179], v[208:211], v[20:23]
	v_mfma_f32_16x16x32_bf16 v[20:23], v[180:183], v[212:215], v[20:23]
	v_mfma_f32_16x16x32_bf16 v[4:7], v[176:179], v[216:219], v[4:7]
	v_mfma_f32_16x16x32_bf16 v[4:7], v[180:183], v[220:223], v[4:7]
	v_mfma_f32_16x16x32_bf16 v[0:3], v[184:187], v[216:219], v[0:3]
	v_mfma_f32_16x16x32_bf16 v[0:3], v[188:191], v[220:223], v[0:3]
	v_mfma_f32_16x16x32_bf16 v[16:19], v[184:187], v[208:211], v[16:19]
	v_mfma_f32_16x16x32_bf16 v[16:19], v[188:191], v[212:215], v[16:19]
	s_setprio 2
	s_barrier
	v_mfma_f32_16x16x32_bf16 v[32:35], v[184:187], v[200:203], v[32:35]
	v_mfma_f32_16x16x32_bf16 v[32:35], v[188:191], v[204:207], v[32:35]
	v_mfma_f32_16x16x32_bf16 v[48:51], v[184:187], v[192:195], v[48:51]
	v_mfma_f32_16x16x32_bf16 v[48:51], v[188:191], v[196:199], v[48:51]
	s_setprio 0
	s_add_i32 s90, s90, 2
	s_add_u32 s74, s74, 0x100
	s_addc_u32 s75, s75, 0
	s_add_u32 s88, s88, 0x100
	s_addc_u32 s89, s89, 0
	s_cmp_gt_u32 s90, 27
	s_cbranch_scc0 .LBB0_102
	ds_read_b128 v[160:163], v155
	ds_read_b128 v[164:167], v155 offset:1024
	ds_read_b128 v[168:171], v155 offset:2048
	ds_read_b128 v[172:175], v155 offset:3072
	ds_read_b128 v[176:179], v157
	ds_read_b128 v[180:183], v157 offset:1024
	ds_read_b128 v[184:187], v157 offset:2048
	ds_read_b128 v[188:191], v157 offset:3072
	s_add_u32 s62, s74, 0xfff80080
	s_addc_u32 s63, s75, -1
	s_cmp_eq_u32 s90, 28
	s_cselect_b32 s79, s10, s63
	s_cselect_b32 s78, s11, s62
	s_cselect_b32 s77, s51, s89
	s_cselect_b32 s76, s55, s88
	v_lshl_add_u64 v[224:225], s[74:75], 0, v[138:139]
	s_add_i32 m0, s61, 0xc000
	ds_read_b128 v[192:195], v159
	ds_read_b128 v[196:199], v159 offset:1024
	ds_read_b128 v[200:203], v159 offset:2048
	ds_read_b128 v[204:207], v159 offset:3072
	ds_read_b128 v[208:211], v159 offset:4096
	ds_read_b128 v[212:215], v159 offset:5120
	ds_read_b128 v[216:219], v159 offset:6144
	ds_read_b128 v[220:223], v159 offset:7168
	global_load_lds_dwordx4 v[224:225], off
	v_lshl_add_u64 v[224:225], s[74:75], 0, v[140:141]
	s_add_i32 m0, s61, 0xe000
	s_nop 0
	global_load_lds_dwordx4 v[224:225], off
	s_waitcnt vmcnt(8)
	s_waitcnt lgkmcnt(0)
	s_setprio 1
	s_barrier
; #define PG8_STAGE(bufoff, gbase, voff) do { _Pragma("unroll") for (int _i = 0; _i < 2; ++_i) \
;         __builtin_amdgcn_global_load_lds((const unsigned*)((const char*)(gbase) + (voff)[_i]), (PG8_LAS unsigned*)(lds + (bufoff) + ldsw + _i * 8192), 16, 0, 0); } while (0)
; #define PG8_LDA(dst, b, h) do { _Pragma("unroll") for (int m = 0; m < 4; ++m) _Pragma("unroll") for (int k = 0; k < 2; ++k) dst[m][k] = *(const PG8_LAS bf16x8*)(lds + PG8_SA(b, h) + aoff + m * 2048 + k * 1024); } while (0)
; #define PG8_LDB(dst, b, h) do { _Pragma("unroll") for (int n = 0; n < 2; ++n) _Pragma("unroll") for (int k = 0; k < 2; ++k) dst[n][k] = *(const PG8_LAS bf16x8*)(lds + PG8_SB(b, h) + boff + n * 2048 + k * 1024); } while (0)
; #define PG8_MMA(ai, bj, At, Bt) do { __builtin_amdgcn_s_setprio(1); _Pragma("unroll") for (int m = 0; m < 4; ++m) _Pragma("unroll") for (int n = 0; n < 2; ++n) _Pragma("unroll") for (int k = 0; k < 2; ++k) \
;         acc[ai][bj][m][n] = __builtin_amdgcn_mfma_f32_16x16x32_bf16(Bt[n][k], At[m][k], acc[ai][bj][m][n], 0, 0, 0); __builtin_amdgcn_s_setprio(0); } while (0)
; #define PG8_WAIT_V(n) asm volatile("s_waitcnt vmcnt(" #n ")" ::: "memory")
; #define PG8_WAIT_L(n) asm volatile("s_waitcnt lgkmcnt(" #n ")" ::: "memory")
; #define PG8_BAR __builtin_amdgcn_s_barrier()
; #define PG8_SCHED __builtin_amdgcn_sched_barrier(0)
; template <class Epi, class Sched, bool ALIGN_EPI = false, bool SP2 = false>
; __device__ __forceinline__ void gemm_phase(PG8_LAS unsigned char* lds, const Gemm g, const Sched& S, const Epi& E) {
;     ...
;             PG8_LDB(B0, 0, 0); PG8_LDB(B1, 0, 1); PG8_SCHED; PG8_LDA(At, 0, 0); PG8_STAGE(PG8_SA(1, 1), a1 + hstep, voffA);
;             PG8_WAIT_V(8); PG8_WAIT_L(0); PG8_BAR; PG8_MMA(0, 0, At, B0); PG8_MMA(0, 1, At, B1); PG8_BAR; PG8_SCHED;
;             PG8_LDA(At, 0, 1); PG8_STAGE(PG8_SB(0, 0), b2, voffB); PG8_STAGE(PG8_SB(0, 1), b2 + hstep, voffB); PG8_STAGE(PG8_SA(0, 0), a2, voffA);
;             PG8_WAIT_V(8); PG8_WAIT_L(0); PG8_BAR; PG8_MMA(1, 0, At, B0); PG8_MMA(1, 1, At, B1); PG8_BAR; PG8_SCHED;
;             PG8_LDB(B0, 1, 0); PG8_LDB(B1, 1, 1); PG8_SCHED; PG8_LDA(At, 1, 0); PG8_STAGE(PG8_SA(0, 1), a2 + hstep, voffA);
;             PG8_WAIT_V(8); PG8_WAIT_L(0); PG8_BAR; PG8_MMA(0, 0, At, B0); PG8_MMA(0, 1, At, B1); PG8_BAR; PG8_SCHED;
	v_mfma_f32_16x16x32_bf16 v[124:127], v[160:163], v[192:195], v[124:127]
	v_mfma_f32_16x16x32_bf16 v[124:127], v[164:167], v[196:199], v[124:127]
	v_mfma_f32_16x16x32_bf16 v[108:111], v[160:163], v[200:203], v[108:111]
	v_mfma_f32_16x16x32_bf16 v[108:111], v[164:167], v[204:207], v[108:111]
	v_mfma_f32_16x16x32_bf16 v[92:95], v[160:163], v[208:211], v[92:95]
	v_mfma_f32_16x16x32_bf16 v[92:95], v[164:167], v[212:215], v[92:95]
	v_mfma_f32_16x16x32_bf16 v[76:79], v[160:163], v[216:219], v[76:79]
	v_mfma_f32_16x16x32_bf16 v[76:79], v[164:167], v[220:223], v[76:79]
	v_mfma_f32_16x16x32_bf16 v[72:75], v[168:171], v[216:219], v[72:75]
	v_mfma_f32_16x16x32_bf16 v[72:75], v[172:175], v[220:223], v[72:75]
	v_mfma_f32_16x16x32_bf16 v[88:91], v[168:171], v[208:211], v[88:91]
	v_mfma_f32_16x16x32_bf16 v[88:91], v[172:175], v[212:215], v[88:91]
	v_mfma_f32_16x16x32_bf16 v[104:107], v[168:171], v[200:203], v[104:107]
	v_mfma_f32_16x16x32_bf16 v[104:107], v[172:175], v[204:207], v[104:107]
	v_mfma_f32_16x16x32_bf16 v[120:123], v[168:171], v[192:195], v[120:123]
	v_mfma_f32_16x16x32_bf16 v[120:123], v[172:175], v[196:199], v[120:123]
	v_mfma_f32_16x16x32_bf16 v[116:119], v[176:179], v[192:195], v[116:119]
	v_mfma_f32_16x16x32_bf16 v[116:119], v[180:183], v[196:199], v[116:119]
	v_mfma_f32_16x16x32_bf16 v[100:103], v[176:179], v[200:203], v[100:103]
	v_mfma_f32_16x16x32_bf16 v[100:103], v[180:183], v[204:207], v[100:103]
	v_mfma_f32_16x16x32_bf16 v[84:87], v[176:179], v[208:211], v[84:87]
	v_mfma_f32_16x16x32_bf16 v[84:87], v[180:183], v[212:215], v[84:87]
	v_mfma_f32_16x16x32_bf16 v[68:71], v[176:179], v[216:219], v[68:71]
	v_mfma_f32_16x16x32_bf16 v[68:71], v[180:183], v[220:223], v[68:71]
	v_mfma_f32_16x16x32_bf16 v[64:67], v[184:187], v[216:219], v[64:67]
	v_mfma_f32_16x16x32_bf16 v[64:67], v[188:191], v[220:223], v[64:67]
	v_mfma_f32_16x16x32_bf16 v[80:83], v[184:187], v[208:211], v[80:83]
	v_mfma_f32_16x16x32_bf16 v[80:83], v[188:191], v[212:215], v[80:83]
	s_setprio 2
	s_barrier
	v_mfma_f32_16x16x32_bf16 v[96:99], v[184:187], v[200:203], v[96:99]
	v_mfma_f32_16x16x32_bf16 v[96:99], v[188:191], v[204:207], v[96:99]
	v_mfma_f32_16x16x32_bf16 v[112:115], v[184:187], v[192:195], v[112:115]
	v_mfma_f32_16x16x32_bf16 v[112:115], v[188:191], v[196:199], v[112:115]
	s_setprio 0
	s_add_i32 s62, s84, s35
	v_lshl_add_u64 v[224:225], s[76:77], 0, v[130:131]
	s_mov_b32 m0, s62
	ds_read_b128 v[192:195], v159 offset:16384
	ds_read_b128 v[196:199], v159 offset:17408
	ds_read_b128 v[200:203], v159 offset:18432
	ds_read_b128 v[204:207], v159 offset:19456
	ds_read_b128 v[208:211], v159 offset:20480
	ds_read_b128 v[212:215], v159 offset:21504
	ds_read_b128 v[216:219], v159 offset:22528
	ds_read_b128 v[220:223], v159 offset:23552
	global_load_lds_dwordx4 v[224:225], off
	s_add_i32 m0, s62, 0x2000
	s_add_u32 s92, s76, 0x80000
	v_lshl_add_u64 v[226:227], s[76:77], 0, v[134:135]
	s_addc_u32 s93, s77, 0
	s_add_i32 s62, s85, s35
	global_load_lds_dwordx4 v[226:227], off
	v_lshl_add_u64 v[228:229], s[92:93], 0, v[130:131]
	s_mov_b32 m0, s62
	v_lshl_add_u64 v[230:231], s[78:79], 0, v[132:133]
	global_load_lds_dwordx4 v[228:229], off
	v_lshl_add_u64 v[228:229], s[92:93], 0, v[134:135]
	s_add_i32 m0, s62, 0x2000
	s_nop 0
	global_load_lds_dwordx4 v[228:229], off
	v_lshl_add_u64 v[228:229], s[78:79], 0, v[128:129]
	s_mov_b32 m0, s61
	s_nop 0
	global_load_lds_dwordx4 v[228:229], off
	s_mov_b32 m0, s65
	s_nop 0
	global_load_lds_dwordx4 v[230:231], off
	s_waitcnt vmcnt(8)
	s_waitcnt lgkmcnt(0)
	s_setprio 1
	s_barrier
	v_mfma_f32_16x16x32_bf16 v[60:63], v[160:163], v[192:195], v[60:63]
	v_mfma_f32_16x16x32_bf16 v[60:63], v[164:167], v[196:199], v[60:63]
	v_mfma_f32_16x16x32_bf16 v[44:47], v[160:163], v[200:203], v[44:47]
	v_mfma_f32_16x16x32_bf16 v[44:47], v[164:167], v[204:207], v[44:47]
	v_mfma_f32_16x16x32_bf16 v[28:31], v[160:163], v[208:211], v[28:31]
	v_mfma_f32_16x16x32_bf16 v[28:31], v[164:167], v[212:215], v[28:31]
	v_mfma_f32_16x16x32_bf16 v[12:15], v[160:163], v[216:219], v[12:15]
	v_mfma_f32_16x16x32_bf16 v[12:15], v[164:167], v[220:223], v[12:15]
	v_mfma_f32_16x16x32_bf16 v[8:11], v[168:171], v[216:219], v[8:11]
	v_mfma_f32_16x16x32_bf16 v[8:11], v[172:175], v[220:223], v[8:11]
	v_mfma_f32_16x16x32_bf16 v[24:27], v[168:171], v[208:211], v[24:27]
	v_mfma_f32_16x16x32_bf16 v[24:27], v[172:175], v[212:215], v[24:27]
	v_mfma_f32_16x16x32_bf16 v[40:43], v[168:171], v[200:203], v[40:43]
	v_mfma_f32_16x16x32_bf16 v[40:43], v[172:175], v[204:207], v[40:43]
	v_mfma_f32_16x16x32_bf16 v[56:59], v[168:171], v[192:195], v[56:59]
	v_mfma_f32_16x16x32_bf16 v[56:59], v[172:175], v[196:199], v[56:59]
	v_mfma_f32_16x16x32_bf16 v[52:55], v[176:179], v[192:195], v[52:55]
	v_mfma_f32_16x16x32_bf16 v[52:55], v[180:183], v[196:199], v[52:55]
	v_mfma_f32_16x16x32_bf16 v[36:39], v[176:179], v[200:203], v[36:39]
	v_mfma_f32_16x16x32_bf16 v[36:39], v[180:183], v[204:207], v[36:39]
	v_mfma_f32_16x16x32_bf16 v[20:23], v[176:179], v[208:211], v[20:23]
	v_mfma_f32_16x16x32_bf16 v[20:23], v[180:183], v[212:215], v[20:23]
	v_mfma_f32_16x16x32_bf16 v[4:7], v[176:179], v[216:219], v[4:7]
	v_mfma_f32_16x16x32_bf16 v[4:7], v[180:183], v[220:223], v[4:7]
	v_mfma_f32_16x16x32_bf16 v[0:3], v[184:187], v[216:219], v[0:3]
	v_mfma_f32_16x16x32_bf16 v[0:3], v[188:191], v[220:223], v[0:3]
	v_mfma_f32_16x16x32_bf16 v[16:19], v[184:187], v[208:211], v[16:19]
	v_mfma_f32_16x16x32_bf16 v[16:19], v[188:191], v[212:215], v[16:19]
	s_setprio 2
	s_barrier
; #define PG8_STAGE(bufoff, gbase, voff) do { _Pragma("unroll") for (int _i = 0; _i < 2; ++_i) \
;         __builtin_amdgcn_global_load_lds((const unsigned*)((const char*)(gbase) + (voff)[_i]), (PG8_LAS unsigned*)(lds + (bufoff) + ldsw + _i * 8192), 16, 0, 0); } while (0)
; #define PG8_LDA(dst, b, h) do { _Pragma("unroll") for (int m = 0; m < 4; ++m) _Pragma("unroll") for (int k = 0; k < 2; ++k) dst[m][k] = *(const PG8_LAS bf16x8*)(lds + PG8_SA(b, h) + aoff + m * 2048 + k * 1024); } while (0)
; #define PG8_LDB(dst, b, h) do { _Pragma("unroll") for (int n = 0; n < 2; ++n) _Pragma("unroll") for (int k = 0; k < 2; ++k) dst[n][k] = *(const PG8_LAS bf16x8*)(lds + PG8_SB(b, h) + boff + n * 2048 + k * 1024); } while (0)
; #define PG8_MMA(ai, bj, At, Bt) do { __builtin_amdgcn_s_setprio(1); _Pragma("unroll") for (int m = 0; m < 4; ++m) _Pragma("unroll") for (int n = 0; n < 2; ++n) _Pragma("unroll") for (int k = 0; k < 2; ++k) \
;         acc[ai][bj][m][n] = __builtin_amdgcn_mfma_f32_16x16x32_bf16(Bt[n][k], At[m][k], acc[ai][bj][m][n], 0, 0, 0); __builtin_amdgcn_s_setprio(0); } while (0)
; #define PG8_WAIT_V(n) asm volatile("s_waitcnt vmcnt(" #n ")" ::: "memory")
; #define PG8_WAIT_L(n) asm volatile("s_waitcnt lgkmcnt(" #n ")" ::: "memory")
; #define PG8_BAR __builtin_amdgcn_s_barrier()
; #define PG8_SCHED __builtin_amdgcn_sched_barrier(0)
; __device__ __forceinline__ float silu_mul(float g, float u) {
;     const float e = __builtin_amdgcn_exp2f(g * -1.4426950408889634f);
;     return g * __builtin_amdgcn_rcpf(1.0f + e) * u;
; template <class Epi, class Sched, bool ALIGN_EPI = false, bool SP2 = false>
; __device__ __forceinline__ void gemm_phase(PG8_LAS unsigned char* lds, const Gemm g, const Sched& S, const Epi& E) {
;     ...
;             PG8_LDB(B0, 1, 0); PG8_LDB(B1, 1, 1); PG8_SCHED; PG8_LDA(At, 1, 0); PG8_STAGE(PG8_SA(0, 1), a2 + hstep, voffA);
;             PG8_WAIT_V(8); PG8_WAIT_L(0); PG8_BAR; PG8_MMA(0, 0, At, B0); PG8_MMA(0, 1, At, B1); PG8_BAR; PG8_SCHED;
;             PG8_LDA(At, 1, 1); PG8_STAGE(PG8_SB(1, 0), b3, voffB); PG8_STAGE(PG8_SB(1, 1), b3 + hstep, voffB); PG8_STAGE(PG8_SA(1, 0), a3, voffA);
;             PG8_WAIT_V(8); PG8_WAIT_L(0); PG8_BAR; PG8_MMA(1, 0, At, B0); PG8_MMA(1, 1, At, B1); PG8_BAR; PG8_SCHED;
	v_mfma_f32_16x16x32_bf16 v[32:35], v[184:187], v[200:203], v[32:35]
	v_mfma_f32_16x16x32_bf16 v[32:35], v[188:191], v[204:207], v[32:35]
	v_mfma_f32_16x16x32_bf16 v[48:51], v[184:187], v[192:195], v[48:51]
	v_mfma_f32_16x16x32_bf16 v[48:51], v[188:191], v[196:199], v[48:51]
	s_setprio 0
	s_add_i32 s62, 0, 0x18000
	s_add_i32 s63, 0, 0x1c000
	v_add_u32_e32 v172, s62, v147
	v_add_u32_e32 v188, s63, v147
	ds_read_b128 v[160:163], v172
	ds_read_b128 v[164:167], v172 offset:1024
	ds_read_b128 v[168:171], v172 offset:2048
	ds_read_b128 v[172:175], v172 offset:3072
	ds_read_b128 v[176:179], v188
	ds_read_b128 v[180:183], v188 offset:1024
	ds_read_b128 v[184:187], v188 offset:2048
	ds_read_b128 v[188:191], v188 offset:3072
	s_add_u32 s78, s78, 0x80000
	s_addc_u32 s79, s79, 0
	s_mov_b32 m0, s66
	v_lshl_add_u64 v[232:233], s[78:79], 0, v[128:129]
	ds_read_b128 v[192:195], v159 offset:32768
	ds_read_b128 v[196:199], v159 offset:33792
	ds_read_b128 v[200:203], v159 offset:34816
	ds_read_b128 v[204:207], v159 offset:35840
	ds_read_b128 v[208:211], v159 offset:36864
	ds_read_b128 v[212:215], v159 offset:37888
	ds_read_b128 v[216:219], v159 offset:38912
	ds_read_b128 v[220:223], v159 offset:39936
	global_load_lds_dwordx4 v[232:233], off
	v_lshl_add_u64 v[232:233], s[78:79], 0, v[132:133]
	s_mov_b32 m0, s67
	s_nop 0
	global_load_lds_dwordx4 v[232:233], off
	s_waitcnt vmcnt(8)
	s_waitcnt lgkmcnt(0)
	s_setprio 1
	s_barrier
	v_mfma_f32_16x16x32_bf16 v[124:127], v[160:163], v[192:195], v[124:127]
	v_mfma_f32_16x16x32_bf16 v[124:127], v[164:167], v[196:199], v[124:127]
	v_mfma_f32_16x16x32_bf16 v[108:111], v[160:163], v[200:203], v[108:111]
	v_mfma_f32_16x16x32_bf16 v[108:111], v[164:167], v[204:207], v[108:111]
	v_mfma_f32_16x16x32_bf16 v[92:95], v[160:163], v[208:211], v[92:95]
	v_mfma_f32_16x16x32_bf16 v[92:95], v[164:167], v[212:215], v[92:95]
	v_mfma_f32_16x16x32_bf16 v[76:79], v[160:163], v[216:219], v[76:79]
	v_mfma_f32_16x16x32_bf16 v[76:79], v[164:167], v[220:223], v[76:79]
	v_mfma_f32_16x16x32_bf16 v[72:75], v[168:171], v[216:219], v[72:75]
	v_mfma_f32_16x16x32_bf16 v[72:75], v[172:175], v[220:223], v[72:75]
	v_mfma_f32_16x16x32_bf16 v[88:91], v[168:171], v[208:211], v[88:91]
	v_mfma_f32_16x16x32_bf16 v[88:91], v[172:175], v[212:215], v[88:91]
	v_mfma_f32_16x16x32_bf16 v[104:107], v[168:171], v[200:203], v[104:107]
	v_mfma_f32_16x16x32_bf16 v[104:107], v[172:175], v[204:207], v[104:107]
	v_mfma_f32_16x16x32_bf16 v[120:123], v[168:171], v[192:195], v[120:123]
	v_mfma_f32_16x16x32_bf16 v[120:123], v[172:175], v[196:199], v[120:123]
	v_mfma_f32_16x16x32_bf16 v[116:119], v[176:179], v[192:195], v[116:119]
	v_mfma_f32_16x16x32_bf16 v[116:119], v[180:183], v[196:199], v[116:119]
	v_mfma_f32_16x16x32_bf16 v[100:103], v[176:179], v[200:203], v[100:103]
	v_mfma_f32_16x16x32_bf16 v[100:103], v[180:183], v[204:207], v[100:103]
	v_mfma_f32_16x16x32_bf16 v[84:87], v[176:179], v[208:211], v[84:87]
	v_mfma_f32_16x16x32_bf16 v[84:87], v[180:183], v[212:215], v[84:87]
	v_mfma_f32_16x16x32_bf16 v[68:71], v[176:179], v[216:219], v[68:71]
	v_mfma_f32_16x16x32_bf16 v[68:71], v[180:183], v[220:223], v[68:71]
	v_mfma_f32_16x16x32_bf16 v[64:67], v[184:187], v[216:219], v[64:67]
	v_mfma_f32_16x16x32_bf16 v[64:67], v[188:191], v[220:223], v[64:67]
	v_mfma_f32_16x16x32_bf16 v[80:83], v[184:187], v[208:211], v[80:83]
	v_mfma_f32_16x16x32_bf16 v[80:83], v[188:191], v[212:215], v[80:83]
	s_setprio 2
	s_barrier
	v_mfma_f32_16x16x32_bf16 v[96:99], v[184:187], v[200:203], v[96:99]
	v_mfma_f32_16x16x32_bf16 v[96:99], v[188:191], v[204:207], v[96:99]
	v_mfma_f32_16x16x32_bf16 v[112:115], v[184:187], v[192:195], v[112:115]
	v_mfma_f32_16x16x32_bf16 v[112:115], v[188:191], v[196:199], v[112:115]
	s_setprio 0
	s_add_i32 s62, s62, s35
	v_lshl_add_u64 v[224:225], v[224:225], 0, s[18:19]
	s_mov_b32 m0, s62
	ds_read_b128 v[192:195], v159 offset:49152
	ds_read_b128 v[196:199], v159 offset:50176
	ds_read_b128 v[200:203], v159 offset:51200
	ds_read_b128 v[204:207], v159 offset:52224
	ds_read_b128 v[208:211], v159 offset:53248
	ds_read_b128 v[212:215], v159 offset:54272
	ds_read_b128 v[216:219], v159 offset:55296
	ds_read_b128 v[220:223], v159 offset:56320
	global_load_lds_dwordx4 v[224:225], off
	s_add_i32 m0, s62, 0x2000
	s_add_u32 s76, s76, 0x80080
	v_lshl_add_u64 v[224:225], v[226:227], 0, s[18:19]
	s_addc_u32 s77, s77, 0
	s_add_i32 s62, s63, s35
	global_load_lds_dwordx4 v[224:225], off
	v_lshl_add_u64 v[224:225], s[76:77], 0, v[130:131]
	s_mov_b32 m0, s62
	s_nop 0
	global_load_lds_dwordx4 v[224:225], off
	v_lshl_add_u64 v[224:225], s[76:77], 0, v[134:135]
	s_add_i32 m0, s62, 0x2000
	s_nop 0
	global_load_lds_dwordx4 v[224:225], off
	v_lshl_add_u64 v[224:225], v[228:229], 0, s[18:19]
	s_mov_b32 m0, s81
	s_nop 0
	global_load_lds_dwordx4 v[224:225], off
	v_lshl_add_u64 v[224:225], v[230:231], 0, s[18:19]
	s_mov_b32 m0, s82
	s_nop 0
	global_load_lds_dwordx4 v[224:225], off
	v_mov_b32_e32 v240, 0xbfb8aa3b
	v_mov_b32_e32 v241, 0xbfb8aa3b
	v_mov_b32_e32 v242, 1.0
	v_mov_b32_e32 v243, 1.0
	s_waitcnt vmcnt(8)
	s_waitcnt lgkmcnt(0)
	s_setprio 1
	s_barrier
; __device__ __forceinline__ unsigned cvt_pk_bf16(float lo, float hi) { unsigned r; asm volatile("v_cvt_pk_bf16_f32 %0, %1, %2" : "=v"(r) : "v"(lo), "v"(hi)); return r; }
; __device__ __forceinline__ float silu_mul(float g, float u) {
;     const float e = __builtin_amdgcn_exp2f(g * -1.4426950408889634f);
;     return g * __builtin_amdgcn_rcpf(1.0f + e) * u;
; }
;     __device__ __forceinline__ void pre(const Unit& u, int wr, int fr, float (&rv)[8]) const {
; #pragma unroll
;         for (int i = 0; i < 8; ++i) rv[i] = rs[u.pm * BM + wr * 64 + fr + (i >> 2) * HALF + (i & 3) * 16];
;     }
;     __device__ __forceinline__ void operator()(const f32x4 (&acc)[2][2][4][2], const Unit& u, int wr, int wc, int fr, int fq, const float (&rv)[8]) const {
;         const int row0 = u.pm * BM + wr * 64 + fr, col0 = u.pn * HALF + wc * 32 + 8 * fq;
; #pragma unroll
;         for (int ai = 0; ai < 2; ++ai)
; #pragma unroll
;             for (int m = 0; m < 4; ++m) {
;                 bf16_t* rowp = O + (size_t)(row0 + ai * HALF + m * 16) * ldc + col0;
;                 const float r = rv[ai * 4 + m];
;                 const f32x4 g0 = acc[ai][0][m][0] * r, g1 = acc[ai][0][m][1] * r, u0 = acc[ai][1][m][0] * r, u1 = acc[ai][1][m][1] * r;
;                 u32x4 w;
;                 w.x = cvt_pk_bf16(silu_mul(g0[0], u0[0]), silu_mul(g0[1], u0[1]));
;                 w.y = cvt_pk_bf16(silu_mul(g0[2], u0[2]), silu_mul(g0[3], u0[3]));
;                 w.z = cvt_pk_bf16(silu_mul(g1[0], u1[0]), silu_mul(g1[1], u1[1]));
;                 w.w = cvt_pk_bf16(silu_mul(g1[2], u1[2]), silu_mul(g1[3], u1[3]));
	v_mfma_f32_16x16x32_bf16 v[60:63], v[160:163], v[192:195], v[60:63]
	v_mfma_f32_16x16x32_bf16 v[60:63], v[164:167], v[196:199], v[60:63]
	v_pk_mul_f32 v[124:125], v[158:159], v[124:125] op_sel_hi:[0,1]
	v_pk_mul_f32 v[116:117], v[158:159], v[116:117] op_sel_hi:[0,1]
	v_pk_mul_f32 v[126:127], v[158:159], v[126:127] op_sel_hi:[0,1]
	v_pk_mul_f32 v[118:119], v[158:159], v[118:119] op_sel_hi:[0,1]
	v_mfma_f32_16x16x32_bf16 v[44:47], v[160:163], v[200:203], v[44:47]
	v_mfma_f32_16x16x32_bf16 v[44:47], v[164:167], v[204:207], v[44:47]
	v_pk_mul_f32 v[246:247], v[124:125], v[240:241]
	v_pk_mul_f32 v[248:249], v[126:127], v[240:241]
	v_exp_f32_e32 v246, v246
	v_exp_f32_e32 v247, v247
	v_mfma_f32_16x16x32_bf16 v[28:31], v[160:163], v[208:211], v[28:31]
	v_mfma_f32_16x16x32_bf16 v[28:31], v[164:167], v[212:215], v[28:31]
	v_exp_f32_e32 v248, v248
	v_exp_f32_e32 v249, v249
	v_pk_add_f32 v[246:247], v[246:247], v[242:243]
	v_pk_add_f32 v[248:249], v[248:249], v[242:243]
	v_mfma_f32_16x16x32_bf16 v[12:15], v[160:163], v[216:219], v[12:15]
	v_mfma_f32_16x16x32_bf16 v[12:15], v[164:167], v[220:223], v[12:15]
	v_rcp_f32_e32 v246, v246
	v_rcp_f32_e32 v247, v247
	v_rcp_f32_e32 v248, v248
	v_rcp_f32_e32 v249, v249
	v_mfma_f32_16x16x32_bf16 v[8:11], v[168:171], v[216:219], v[8:11]
	v_mfma_f32_16x16x32_bf16 v[8:11], v[172:175], v[220:223], v[8:11]
	v_pk_mul_f32 v[124:125], v[124:125], v[246:247]
	v_pk_mul_f32 v[126:127], v[126:127], v[248:249]
	v_pk_mul_f32 v[124:125], v[124:125], v[116:117]
	v_pk_mul_f32 v[126:127], v[126:127], v[118:119]
	v_mfma_f32_16x16x32_bf16 v[24:27], v[168:171], v[208:211], v[24:27]
	v_mfma_f32_16x16x32_bf16 v[24:27], v[172:175], v[212:215], v[24:27]
	v_pk_mul_f32 v[120:121], v[158:159], v[120:121] op_sel_hi:[0,1]
	v_pk_mul_f32 v[112:113], v[158:159], v[112:113] op_sel_hi:[0,1]
	v_pk_mul_f32 v[122:123], v[158:159], v[122:123] op_sel_hi:[0,1]
	v_pk_mul_f32 v[114:115], v[158:159], v[114:115] op_sel_hi:[0,1]
	v_mfma_f32_16x16x32_bf16 v[40:43], v[168:171], v[200:203], v[40:43]
	v_mfma_f32_16x16x32_bf16 v[40:43], v[172:175], v[204:207], v[40:43]
	v_pk_mul_f32 v[246:247], v[120:121], v[240:241]
	v_pk_mul_f32 v[248:249], v[122:123], v[240:241]
	v_exp_f32_e32 v246, v246
	v_exp_f32_e32 v247, v247
	v_mfma_f32_16x16x32_bf16 v[56:59], v[168:171], v[192:195], v[56:59]
	v_mfma_f32_16x16x32_bf16 v[56:59], v[172:175], v[196:199], v[56:59]
	v_exp_f32_e32 v248, v248
	v_exp_f32_e32 v249, v249
	v_pk_add_f32 v[246:247], v[246:247], v[242:243]
	v_pk_add_f32 v[248:249], v[248:249], v[242:243]
	v_mfma_f32_16x16x32_bf16 v[52:55], v[176:179], v[192:195], v[52:55]
	v_mfma_f32_16x16x32_bf16 v[52:55], v[180:183], v[196:199], v[52:55]
	v_rcp_f32_e32 v246, v246
	v_rcp_f32_e32 v247, v247
	v_rcp_f32_e32 v248, v248
	v_rcp_f32_e32 v249, v249
	v_mfma_f32_16x16x32_bf16 v[36:39], v[176:179], v[200:203], v[36:39]
	v_mfma_f32_16x16x32_bf16 v[36:39], v[180:183], v[204:207], v[36:39]
	v_pk_mul_f32 v[120:121], v[120:121], v[246:247]
	v_pk_mul_f32 v[122:123], v[122:123], v[248:249]
	v_pk_mul_f32 v[120:121], v[120:121], v[112:113]
	v_pk_mul_f32 v[122:123], v[122:123], v[114:115]
	v_mfma_f32_16x16x32_bf16 v[20:23], v[176:179], v[208:211], v[20:23]
	v_mfma_f32_16x16x32_bf16 v[20:23], v[180:183], v[212:215], v[20:23]
	v_cvt_pk_bf16_f32 v112, v124, v125
	v_cvt_pk_bf16_f32 v113, v126, v127
	v_cvt_pk_bf16_f32 v114, v120, v121
	v_cvt_pk_bf16_f32 v115, v122, v123
	v_mfma_f32_16x16x32_bf16 v[4:7], v[176:179], v[216:219], v[4:7]
	v_mfma_f32_16x16x32_bf16 v[4:7], v[180:183], v[220:223], v[4:7]
	v_pk_mul_f32 v[108:109], v[156:157], v[108:109] op_sel_hi:[0,1]
	v_pk_mul_f32 v[100:101], v[156:157], v[100:101] op_sel_hi:[0,1]
	v_pk_mul_f32 v[110:111], v[156:157], v[110:111] op_sel_hi:[0,1]
	v_pk_mul_f32 v[102:103], v[156:157], v[102:103] op_sel_hi:[0,1]
	v_mfma_f32_16x16x32_bf16 v[0:3], v[184:187], v[216:219], v[0:3]
	v_mfma_f32_16x16x32_bf16 v[0:3], v[188:191], v[220:223], v[0:3]
	v_pk_mul_f32 v[246:247], v[108:109], v[240:241]
	v_pk_mul_f32 v[248:249], v[110:111], v[240:241]
	v_exp_f32_e32 v246, v246
	v_exp_f32_e32 v247, v247
	v_mfma_f32_16x16x32_bf16 v[16:19], v[184:187], v[208:211], v[16:19]
	v_mfma_f32_16x16x32_bf16 v[16:19], v[188:191], v[212:215], v[16:19]
	v_exp_f32_e32 v248, v248
	v_exp_f32_e32 v249, v249
	v_pk_add_f32 v[246:247], v[246:247], v[242:243]
	v_pk_add_f32 v[248:249], v[248:249], v[242:243]
	s_setprio 2
	s_barrier
	v_mfma_f32_16x16x32_bf16 v[32:35], v[184:187], v[200:203], v[32:35]
	v_mfma_f32_16x16x32_bf16 v[32:35], v[188:191], v[204:207], v[32:35]
	v_rcp_f32_e32 v246, v246
	v_rcp_f32_e32 v247, v247
	v_rcp_f32_e32 v248, v248
	v_rcp_f32_e32 v249, v249
	v_mfma_f32_16x16x32_bf16 v[48:51], v[184:187], v[192:195], v[48:51]
	v_mfma_f32_16x16x32_bf16 v[48:51], v[188:191], v[196:199], v[48:51]
	v_pk_mul_f32 v[108:109], v[108:109], v[246:247]
	v_pk_mul_f32 v[110:111], v[110:111], v[248:249]
	v_pk_mul_f32 v[108:109], v[108:109], v[100:101]
	v_pk_mul_f32 v[110:111], v[110:111], v[102:103]
	s_setprio 0
	s_add_i32 s90, s90, 2
	s_add_u32 s74, s74, 0x100
	s_addc_u32 s75, s75, 0
	s_add_u32 s88, s88, 0x100
	s_addc_u32 s89, s89, 0
	s_and_b64 vcc, exec, s[22:23]
	s_cbranch_vccz .LBB0_105
	s_barrier
; __device__ __forceinline__ unsigned cvt_pk_bf16(float lo, float hi) { unsigned r; asm volatile("v_cvt_pk_bf16_f32 %0, %1, %2" : "=v"(r) : "v"(lo), "v"(hi)); return r; }
; __device__ __forceinline__ float silu_mul(float g, float u) {
;     const float e = __builtin_amdgcn_exp2f(g * -1.4426950408889634f);
;     return g * __builtin_amdgcn_rcpf(1.0f + e) * u;
; }
;     __device__ __forceinline__ void pre(const Unit& u, int wr, int fr, float (&rv)[8]) const {
; #pragma unroll
;         for (int i = 0; i < 8; ++i) rv[i] = rs[u.pm * BM + wr * 64 + fr + (i >> 2) * HALF + (i & 3) * 16];
;     }
;     __device__ __forceinline__ void operator()(const f32x4 (&acc)[2][2][4][2], const Unit& u, int wr, int wc, int fr, int fq, const float (&rv)[8]) const {
;         const int row0 = u.pm * BM + wr * 64 + fr, col0 = u.pn * HALF + wc * 32 + 8 * fq;
; #pragma unroll
;         for (int ai = 0; ai < 2; ++ai)
; #pragma unroll
;             for (int m = 0; m < 4; ++m) {
;                 bf16_t* rowp = O + (size_t)(row0 + ai * HALF + m * 16) * ldc + col0;
;                 const float r = rv[ai * 4 + m];
;                 const f32x4 g0 = acc[ai][0][m][0] * r, g1 = acc[ai][0][m][1] * r, u0 = acc[ai][1][m][0] * r, u1 = acc[ai][1][m][1] * r;
;                 u32x4 w;
;                 w.x = cvt_pk_bf16(silu_mul(g0[0], u0[0]), silu_mul(g0[1], u0[1]));
;                 w.y = cvt_pk_bf16(silu_mul(g0[2], u0[2]), silu_mul(g0[3], u0[3]));
;                 w.z = cvt_pk_bf16(silu_mul(g1[0], u1[0]), silu_mul(g1[1], u1[1]));
;                 w.w = cvt_pk_bf16(silu_mul(g1[2], u1[2]), silu_mul(g1[3], u1[3]));
;                 *(u32x4*)rowp = w;
.LBB0_105:
	s_waitcnt vmcnt(0)
	v_mov_b32_e32 v240, 0xbfb8aa3b
	v_mov_b32_e32 v241, 0xbfb8aa3b
	v_mov_b32_e32 v242, 1.0
	v_mov_b32_e32 v243, 1.0
	s_nop 7
	s_nop 7
	v_lshl_or_b32 v162, s87, 7, v153
	v_lshl_add_u32 v164, s4, 8, v137
	v_ashrrev_i32_e32 v163, 31, v162
	v_mov_b64_e32 v[160:161], s[14:15]
	v_mad_i64_i32 v[166:167], s[10:11], v164, s86, v[160:161]
	v_lshlrev_b64 v[162:163], 1, v[162:163]
	v_lshl_add_u64 v[166:167], v[166:167], 0, v[162:163]
	global_store_dwordx4 v[166:167], v[112:115], off
	v_pk_mul_f32 v[104:105], v[156:157], v[104:105] op_sel_hi:[0,1]
	v_pk_mul_f32 v[96:97], v[156:157], v[96:97] op_sel_hi:[0,1]
	v_pk_mul_f32 v[106:107], v[156:157], v[106:107] op_sel_hi:[0,1]
	v_pk_mul_f32 v[98:99], v[156:157], v[98:99] op_sel_hi:[0,1]
	v_pk_mul_f32 v[246:247], v[104:105], v[240:241]
	v_pk_mul_f32 v[248:249], v[106:107], v[240:241]
	v_exp_f32_e32 v246, v246
	v_exp_f32_e32 v247, v247
	v_exp_f32_e32 v248, v248
	v_exp_f32_e32 v249, v249
	v_pk_add_f32 v[246:247], v[246:247], v[242:243]
	v_pk_add_f32 v[248:249], v[248:249], v[242:243]
	v_rcp_f32_e32 v246, v246
	v_rcp_f32_e32 v247, v247
	v_rcp_f32_e32 v248, v248
	v_rcp_f32_e32 v249, v249
	v_pk_mul_f32 v[104:105], v[104:105], v[246:247]
	v_pk_mul_f32 v[106:107], v[106:107], v[248:249]
	v_pk_mul_f32 v[104:105], v[104:105], v[96:97]
	v_pk_mul_f32 v[106:107], v[106:107], v[98:99]
	v_or_b32_e32 v112, 16, v164
	v_mad_i64_i32 v[112:113], s[10:11], v112, s86, v[160:161]
	v_lshl_add_u64 v[112:113], v[112:113], 0, v[162:163]
	v_cvt_pk_bf16_f32 v96, v108, v109
	v_cvt_pk_bf16_f32 v97, v110, v111
	v_cvt_pk_bf16_f32 v98, v104, v105
	v_cvt_pk_bf16_f32 v99, v106, v107
	global_store_dwordx4 v[112:113], v[96:99], off
	v_pk_mul_f32 v[92:93], v[154:155], v[92:93] op_sel_hi:[0,1]
	v_pk_mul_f32 v[84:85], v[154:155], v[84:85] op_sel_hi:[0,1]
	v_pk_mul_f32 v[94:95], v[154:155], v[94:95] op_sel_hi:[0,1]
	v_pk_mul_f32 v[86:87], v[154:155], v[86:87] op_sel_hi:[0,1]
	v_pk_mul_f32 v[246:247], v[92:93], v[240:241]
	v_pk_mul_f32 v[248:249], v[94:95], v[240:241]
	v_exp_f32_e32 v246, v246
	v_exp_f32_e32 v247, v247
	v_exp_f32_e32 v248, v248
	v_exp_f32_e32 v249, v249
	v_pk_add_f32 v[246:247], v[246:247], v[242:243]
	v_pk_add_f32 v[248:249], v[248:249], v[242:243]
	v_rcp_f32_e32 v246, v246
	v_rcp_f32_e32 v247, v247
	v_rcp_f32_e32 v248, v248
	v_rcp_f32_e32 v249, v249
	v_pk_mul_f32 v[92:93], v[92:93], v[246:247]
	v_pk_mul_f32 v[94:95], v[94:95], v[248:249]
	v_pk_mul_f32 v[92:93], v[92:93], v[84:85]
	v_pk_mul_f32 v[94:95], v[94:95], v[86:87]
	v_or_b32_e32 v96, 32, v164
	v_mad_i64_i32 v[96:97], s[10:11], v96, s86, v[160:161]
	v_lshl_add_u64 v[96:97], v[96:97], 0, v[162:163]
	v_pk_mul_f32 v[88:89], v[154:155], v[88:89] op_sel_hi:[0,1]
	v_pk_mul_f32 v[80:81], v[154:155], v[80:81] op_sel_hi:[0,1]
	v_pk_mul_f32 v[90:91], v[154:155], v[90:91] op_sel_hi:[0,1]
	v_pk_mul_f32 v[82:83], v[154:155], v[82:83] op_sel_hi:[0,1]
	v_pk_mul_f32 v[246:247], v[88:89], v[240:241]
	v_pk_mul_f32 v[248:249], v[90:91], v[240:241]
	v_exp_f32_e32 v246, v246
	v_exp_f32_e32 v247, v247
	v_exp_f32_e32 v248, v248
	v_exp_f32_e32 v249, v249
	v_pk_add_f32 v[246:247], v[246:247], v[242:243]
	v_pk_add_f32 v[248:249], v[248:249], v[242:243]
	v_rcp_f32_e32 v246, v246
	v_rcp_f32_e32 v247, v247
	v_rcp_f32_e32 v248, v248
	v_rcp_f32_e32 v249, v249
	v_pk_mul_f32 v[88:89], v[88:89], v[246:247]
	v_pk_mul_f32 v[90:91], v[90:91], v[248:249]
	v_pk_mul_f32 v[88:89], v[88:89], v[80:81]
	v_pk_mul_f32 v[90:91], v[90:91], v[82:83]
	v_cvt_pk_bf16_f32 v80, v92, v93
	v_cvt_pk_bf16_f32 v81, v94, v95
	v_cvt_pk_bf16_f32 v82, v88, v89
	v_cvt_pk_bf16_f32 v83, v90, v91
	global_store_dwordx4 v[96:97], v[80:83], off
	v_pk_mul_f32 v[76:77], v[152:153], v[76:77] op_sel_hi:[0,1]
	v_pk_mul_f32 v[68:69], v[152:153], v[68:69] op_sel_hi:[0,1]
	v_pk_mul_f32 v[78:79], v[152:153], v[78:79] op_sel_hi:[0,1]
	v_pk_mul_f32 v[70:71], v[152:153], v[70:71] op_sel_hi:[0,1]
	v_pk_mul_f32 v[246:247], v[76:77], v[240:241]
	v_pk_mul_f32 v[248:249], v[78:79], v[240:241]
	v_exp_f32_e32 v246, v246
	v_exp_f32_e32 v247, v247
	v_exp_f32_e32 v248, v248
	v_exp_f32_e32 v249, v249
	v_pk_add_f32 v[246:247], v[246:247], v[242:243]
	v_pk_add_f32 v[248:249], v[248:249], v[242:243]
	v_rcp_f32_e32 v246, v246
	v_rcp_f32_e32 v247, v247
	v_rcp_f32_e32 v248, v248
	v_rcp_f32_e32 v249, v249
	v_pk_mul_f32 v[76:77], v[76:77], v[246:247]
	v_pk_mul_f32 v[78:79], v[78:79], v[248:249]
	v_pk_mul_f32 v[76:77], v[76:77], v[68:69]
	v_pk_mul_f32 v[78:79], v[78:79], v[70:71]
	v_or_b32_e32 v80, 48, v164
	v_mad_i64_i32 v[80:81], s[10:11], v80, s86, v[160:161]
	v_lshl_add_u64 v[80:81], v[80:81], 0, v[162:163]
	v_pk_mul_f32 v[72:73], v[152:153], v[72:73] op_sel_hi:[0,1]
	v_pk_mul_f32 v[64:65], v[152:153], v[64:65] op_sel_hi:[0,1]
	v_pk_mul_f32 v[74:75], v[152:153], v[74:75] op_sel_hi:[0,1]
	v_pk_mul_f32 v[66:67], v[152:153], v[66:67] op_sel_hi:[0,1]
	v_pk_mul_f32 v[246:247], v[72:73], v[240:241]
	v_pk_mul_f32 v[248:249], v[74:75], v[240:241]
	v_exp_f32_e32 v246, v246
	v_exp_f32_e32 v247, v247
	v_exp_f32_e32 v248, v248
	v_exp_f32_e32 v249, v249
	v_pk_add_f32 v[246:247], v[246:247], v[242:243]
	v_pk_add_f32 v[248:249], v[248:249], v[242:243]
	v_rcp_f32_e32 v246, v246
	v_rcp_f32_e32 v247, v247
	v_rcp_f32_e32 v248, v248
	v_rcp_f32_e32 v249, v249
	v_pk_mul_f32 v[72:73], v[72:73], v[246:247]
	v_pk_mul_f32 v[74:75], v[74:75], v[248:249]
	v_pk_mul_f32 v[72:73], v[72:73], v[64:65]
	v_pk_mul_f32 v[74:75], v[74:75], v[66:67]
	v_cvt_pk_bf16_f32 v64, v76, v77
	v_cvt_pk_bf16_f32 v65, v78, v79
	v_cvt_pk_bf16_f32 v66, v72, v73
	v_cvt_pk_bf16_f32 v67, v74, v75
	global_store_dwordx4 v[80:81], v[64:67], off
	v_pk_mul_f32 v[60:61], v[150:151], v[60:61] op_sel_hi:[0,1]
; __device__ __forceinline__ unsigned cvt_pk_bf16(float lo, float hi) { unsigned r; asm volatile("v_cvt_pk_bf16_f32 %0, %1, %2" : "=v"(r) : "v"(lo), "v"(hi)); return r; }
; __device__ __forceinline__ float silu_mul(float g, float u) {
;     const float e = __builtin_amdgcn_exp2f(g * -1.4426950408889634f);
;     return g * __builtin_amdgcn_rcpf(1.0f + e) * u;
; }
;     __device__ __forceinline__ void pre(const Unit& u, int wr, int fr, float (&rv)[8]) const {
; #pragma unroll
;         for (int i = 0; i < 8; ++i) rv[i] = rs[u.pm * BM + wr * 64 + fr + (i >> 2) * HALF + (i & 3) * 16];
;     }
;     __device__ __forceinline__ void operator()(const f32x4 (&acc)[2][2][4][2], const Unit& u, int wr, int wc, int fr, int fq, const float (&rv)[8]) const {
;         const int row0 = u.pm * BM + wr * 64 + fr, col0 = u.pn * HALF + wc * 32 + 8 * fq;
; #pragma unroll
;         for (int ai = 0; ai < 2; ++ai)
; #pragma unroll
;             for (int m = 0; m < 4; ++m) {
;                 bf16_t* rowp = O + (size_t)(row0 + ai * HALF + m * 16) * ldc + col0;
;                 const float r = rv[ai * 4 + m];
;                 const f32x4 g0 = acc[ai][0][m][0] * r, g1 = acc[ai][0][m][1] * r, u0 = acc[ai][1][m][0] * r, u1 = acc[ai][1][m][1] * r;
;                 u32x4 w;
;                 w.x = cvt_pk_bf16(silu_mul(g0[0], u0[0]), silu_mul(g0[1], u0[1]));
;                 w.y = cvt_pk_bf16(silu_mul(g0[2], u0[2]), silu_mul(g0[3], u0[3]));
;                 w.z = cvt_pk_bf16(silu_mul(g1[0], u1[0]), silu_mul(g1[1], u1[1]));
;                 w.w = cvt_pk_bf16(silu_mul(g1[2], u1[2]), silu_mul(g1[3], u1[3]));
;                 *(u32x4*)rowp = w;
	v_pk_mul_f32 v[52:53], v[150:151], v[52:53] op_sel_hi:[0,1]
	v_pk_mul_f32 v[62:63], v[150:151], v[62:63] op_sel_hi:[0,1]
	v_pk_mul_f32 v[54:55], v[150:151], v[54:55] op_sel_hi:[0,1]
	v_pk_mul_f32 v[246:247], v[60:61], v[240:241]
	v_pk_mul_f32 v[248:249], v[62:63], v[240:241]
	v_exp_f32_e32 v246, v246
	v_exp_f32_e32 v247, v247
	v_exp_f32_e32 v248, v248
	v_exp_f32_e32 v249, v249
	v_pk_add_f32 v[246:247], v[246:247], v[242:243]
	v_pk_add_f32 v[248:249], v[248:249], v[242:243]
	v_rcp_f32_e32 v246, v246
	v_rcp_f32_e32 v247, v247
	v_rcp_f32_e32 v248, v248
	v_rcp_f32_e32 v249, v249
	v_pk_mul_f32 v[60:61], v[60:61], v[246:247]
	v_pk_mul_f32 v[62:63], v[62:63], v[248:249]
	v_pk_mul_f32 v[60:61], v[60:61], v[52:53]
	v_pk_mul_f32 v[62:63], v[62:63], v[54:55]
	v_add_u32_e32 v64, 0x80, v164
	v_mad_i64_i32 v[64:65], s[10:11], v64, s86, v[160:161]
	v_lshl_add_u64 v[64:65], v[64:65], 0, v[162:163]
	v_pk_mul_f32 v[56:57], v[150:151], v[56:57] op_sel_hi:[0,1]
	v_pk_mul_f32 v[48:49], v[150:151], v[48:49] op_sel_hi:[0,1]
	v_pk_mul_f32 v[58:59], v[150:151], v[58:59] op_sel_hi:[0,1]
	v_pk_mul_f32 v[50:51], v[150:151], v[50:51] op_sel_hi:[0,1]
	v_pk_mul_f32 v[246:247], v[56:57], v[240:241]
	v_pk_mul_f32 v[248:249], v[58:59], v[240:241]
	v_exp_f32_e32 v246, v246
	v_exp_f32_e32 v247, v247
	v_exp_f32_e32 v248, v248
	v_exp_f32_e32 v249, v249
	v_pk_add_f32 v[246:247], v[246:247], v[242:243]
	v_pk_add_f32 v[248:249], v[248:249], v[242:243]
	v_rcp_f32_e32 v246, v246
	v_rcp_f32_e32 v247, v247
	v_rcp_f32_e32 v248, v248
	v_rcp_f32_e32 v249, v249
	v_pk_mul_f32 v[56:57], v[56:57], v[246:247]
	v_pk_mul_f32 v[58:59], v[58:59], v[248:249]
	v_pk_mul_f32 v[56:57], v[56:57], v[48:49]
	v_pk_mul_f32 v[58:59], v[58:59], v[50:51]
	v_cvt_pk_bf16_f32 v48, v60, v61
	v_cvt_pk_bf16_f32 v49, v62, v63
	v_cvt_pk_bf16_f32 v50, v56, v57
	v_cvt_pk_bf16_f32 v51, v58, v59
	global_store_dwordx4 v[64:65], v[48:51], off
	v_pk_mul_f32 v[44:45], v[148:149], v[44:45] op_sel_hi:[0,1]
	v_pk_mul_f32 v[36:37], v[148:149], v[36:37] op_sel_hi:[0,1]
	v_pk_mul_f32 v[46:47], v[148:149], v[46:47] op_sel_hi:[0,1]
	v_pk_mul_f32 v[38:39], v[148:149], v[38:39] op_sel_hi:[0,1]
	v_pk_mul_f32 v[246:247], v[44:45], v[240:241]
	v_pk_mul_f32 v[248:249], v[46:47], v[240:241]
	v_exp_f32_e32 v246, v246
	v_exp_f32_e32 v247, v247
	v_exp_f32_e32 v248, v248
	v_exp_f32_e32 v249, v249
	v_pk_add_f32 v[246:247], v[246:247], v[242:243]
	v_pk_add_f32 v[248:249], v[248:249], v[242:243]
	v_rcp_f32_e32 v246, v246
	v_rcp_f32_e32 v247, v247
	v_rcp_f32_e32 v248, v248
	v_rcp_f32_e32 v249, v249
	v_pk_mul_f32 v[44:45], v[44:45], v[246:247]
	v_pk_mul_f32 v[46:47], v[46:47], v[248:249]
	v_pk_mul_f32 v[44:45], v[44:45], v[36:37]
	v_pk_mul_f32 v[46:47], v[46:47], v[38:39]
	v_add_u32_e32 v48, 0x90, v164
	v_mad_i64_i32 v[48:49], s[10:11], v48, s86, v[160:161]
	v_lshl_add_u64 v[48:49], v[48:49], 0, v[162:163]
	v_pk_mul_f32 v[40:41], v[148:149], v[40:41] op_sel_hi:[0,1]
	v_pk_mul_f32 v[32:33], v[148:149], v[32:33] op_sel_hi:[0,1]
	v_pk_mul_f32 v[42:43], v[148:149], v[42:43] op_sel_hi:[0,1]
	v_pk_mul_f32 v[34:35], v[148:149], v[34:35] op_sel_hi:[0,1]
	v_pk_mul_f32 v[246:247], v[40:41], v[240:241]
	v_pk_mul_f32 v[248:249], v[42:43], v[240:241]
	v_exp_f32_e32 v246, v246
	v_exp_f32_e32 v247, v247
	v_exp_f32_e32 v248, v248
	v_exp_f32_e32 v249, v249
	v_pk_add_f32 v[246:247], v[246:247], v[242:243]
	v_pk_add_f32 v[248:249], v[248:249], v[242:243]
	v_rcp_f32_e32 v246, v246
	v_rcp_f32_e32 v247, v247
	v_rcp_f32_e32 v248, v248
	v_rcp_f32_e32 v249, v249
	v_pk_mul_f32 v[40:41], v[40:41], v[246:247]
	v_pk_mul_f32 v[42:43], v[42:43], v[248:249]
	v_pk_mul_f32 v[40:41], v[40:41], v[32:33]
	v_pk_mul_f32 v[42:43], v[42:43], v[34:35]
	v_cvt_pk_bf16_f32 v32, v44, v45
	v_cvt_pk_bf16_f32 v33, v46, v47
	v_cvt_pk_bf16_f32 v34, v40, v41
	v_cvt_pk_bf16_f32 v35, v42, v43
	global_store_dwordx4 v[48:49], v[32:35], off
	v_pk_mul_f32 v[28:29], v[146:147], v[28:29] op_sel_hi:[0,1]
	v_pk_mul_f32 v[20:21], v[146:147], v[20:21] op_sel_hi:[0,1]
	v_pk_mul_f32 v[30:31], v[146:147], v[30:31] op_sel_hi:[0,1]
	v_pk_mul_f32 v[22:23], v[146:147], v[22:23] op_sel_hi:[0,1]
	v_pk_mul_f32 v[246:247], v[28:29], v[240:241]
	v_pk_mul_f32 v[248:249], v[30:31], v[240:241]
; #define PG8_BAR __builtin_amdgcn_s_barrier()
; __device__ __forceinline__ float silu_mul(float g, float u) {
;     const float e = __builtin_amdgcn_exp2f(g * -1.4426950408889634f);
;     return g * __builtin_amdgcn_rcpf(1.0f + e) * u;
; }
;     __device__ __forceinline__ void pre(const Unit& u, int wr, int fr, float (&rv)[8]) const {
; #pragma unroll
;         for (int i = 0; i < 8; ++i) rv[i] = rs[u.pm * BM + wr * 64 + fr + (i >> 2) * HALF + (i & 3) * 16];
;     }
;     __device__ __forceinline__ void operator()(const f32x4 (&acc)[2][2][4][2], const Unit& u, int wr, int wc, int fr, int fq, const float (&rv)[8]) const {
;         const int row0 = u.pm * BM + wr * 64 + fr, col0 = u.pn * HALF + wc * 32 + 8 * fq;
; #pragma unroll
;         for (int ai = 0; ai < 2; ++ai)
; #pragma unroll
;             for (int m = 0; m < 4; ++m) {
;                 bf16_t* rowp = O + (size_t)(row0 + ai * HALF + m * 16) * ldc + col0;
;                 const float r = rv[ai * 4 + m];
;                 const f32x4 g0 = acc[ai][0][m][0] * r, g1 = acc[ai][0][m][1] * r, u0 = acc[ai][1][m][0] * r, u1 = acc[ai][1][m][1] * r;
;                 u32x4 w;
;                 w.x = cvt_pk_bf16(silu_mul(g0[0], u0[0]), silu_mul(g0[1], u0[1]));
;                 w.y = cvt_pk_bf16(silu_mul(g0[2], u0[2]), silu_mul(g0[3], u0[3]));
;                 w.z = cvt_pk_bf16(silu_mul(g1[0], u1[0]), silu_mul(g1[1], u1[1]));
;                 w.w = cvt_pk_bf16(silu_mul(g1[2], u1[2]), silu_mul(g1[3], u1[3]));
;                 *(u32x4*)rowp = w;
; template <class Epi, class Sched, bool ALIGN_EPI = false, bool SP2 = false>
; __device__ __forceinline__ void gemm_phase(PG8_LAS unsigned char* lds, const Gemm g, const Sched& S, const Epi& E) {
;     ...
;         if constexpr (!Epi::AFTER_DRAIN) { E(acc, cur, wr, wc, fr, fq, epre); S.done(cur); }
;         if (!has_next) break;
; #pragma unroll
;         for (int a = 0; a < 2; ++a)
; #pragma unroll
;             for (int b = 0; b < 2; ++b)
; #pragma unroll
;                 for (int m = 0; m < 4; ++m)
; #pragma unroll
;                     for (int n = 0; n < 2; ++n) acc[a][b][m][n] = (f32x4){0.f, 0.f, 0.f, 0.f};
;         cur = nxt; cA = nA; cB = nB; ++ui;
;         E.pre(cur, wr, fr, epre);
;         if constexpr (ALIGN_EPI) { if (wr == 1) PG8_BAR; }
	v_exp_f32_e32 v246, v246
	v_exp_f32_e32 v247, v247
	v_exp_f32_e32 v248, v248
	v_exp_f32_e32 v249, v249
	v_pk_add_f32 v[246:247], v[246:247], v[242:243]
	v_pk_add_f32 v[248:249], v[248:249], v[242:243]
	v_rcp_f32_e32 v246, v246
	v_rcp_f32_e32 v247, v247
	v_rcp_f32_e32 v248, v248
	v_rcp_f32_e32 v249, v249
	v_pk_mul_f32 v[28:29], v[28:29], v[246:247]
	v_pk_mul_f32 v[30:31], v[30:31], v[248:249]
	v_pk_mul_f32 v[28:29], v[28:29], v[20:21]
	v_pk_mul_f32 v[30:31], v[30:31], v[22:23]
	v_add_u32_e32 v32, 0xa0, v164
	v_mad_i64_i32 v[32:33], s[10:11], v32, s86, v[160:161]
	v_lshl_add_u64 v[32:33], v[32:33], 0, v[162:163]
	v_pk_mul_f32 v[24:25], v[146:147], v[24:25] op_sel_hi:[0,1]
	v_pk_mul_f32 v[16:17], v[146:147], v[16:17] op_sel_hi:[0,1]
	v_pk_mul_f32 v[26:27], v[146:147], v[26:27] op_sel_hi:[0,1]
	v_pk_mul_f32 v[18:19], v[146:147], v[18:19] op_sel_hi:[0,1]
	v_pk_mul_f32 v[246:247], v[24:25], v[240:241]
	v_pk_mul_f32 v[248:249], v[26:27], v[240:241]
	v_exp_f32_e32 v246, v246
	v_exp_f32_e32 v247, v247
	v_exp_f32_e32 v248, v248
	v_exp_f32_e32 v249, v249
	v_pk_add_f32 v[246:247], v[246:247], v[242:243]
	v_pk_add_f32 v[248:249], v[248:249], v[242:243]
	v_rcp_f32_e32 v246, v246
	v_rcp_f32_e32 v247, v247
	v_rcp_f32_e32 v248, v248
	v_rcp_f32_e32 v249, v249
	v_pk_mul_f32 v[24:25], v[24:25], v[246:247]
	v_pk_mul_f32 v[26:27], v[26:27], v[248:249]
	v_pk_mul_f32 v[24:25], v[24:25], v[16:17]
	v_pk_mul_f32 v[26:27], v[26:27], v[18:19]
	v_cvt_pk_bf16_f32 v16, v28, v29
	v_cvt_pk_bf16_f32 v17, v30, v31
	v_cvt_pk_bf16_f32 v18, v24, v25
	v_cvt_pk_bf16_f32 v19, v26, v27
	global_store_dwordx4 v[32:33], v[16:19], off
	v_pk_mul_f32 v[12:13], v[136:137], v[12:13] op_sel_hi:[0,1]
	v_pk_mul_f32 v[4:5], v[136:137], v[4:5] op_sel_hi:[0,1]
	v_pk_mul_f32 v[14:15], v[136:137], v[14:15] op_sel_hi:[0,1]
	v_pk_mul_f32 v[6:7], v[136:137], v[6:7] op_sel_hi:[0,1]
	v_pk_mul_f32 v[246:247], v[12:13], v[240:241]
	v_pk_mul_f32 v[248:249], v[14:15], v[240:241]
	v_exp_f32_e32 v246, v246
	v_exp_f32_e32 v247, v247
	v_exp_f32_e32 v248, v248
	v_exp_f32_e32 v249, v249
	v_pk_add_f32 v[246:247], v[246:247], v[242:243]
	v_pk_add_f32 v[248:249], v[248:249], v[242:243]
	v_rcp_f32_e32 v246, v246
	v_rcp_f32_e32 v247, v247
	v_rcp_f32_e32 v248, v248
	v_rcp_f32_e32 v249, v249
	v_pk_mul_f32 v[12:13], v[12:13], v[246:247]
	v_pk_mul_f32 v[14:15], v[14:15], v[248:249]
	v_pk_mul_f32 v[12:13], v[12:13], v[4:5]
	v_pk_mul_f32 v[14:15], v[14:15], v[6:7]
	v_add_u32_e32 v16, 0xb0, v164
	v_mad_i64_i32 v[16:17], s[10:11], v16, s86, v[160:161]
	v_lshl_add_u64 v[16:17], v[16:17], 0, v[162:163]
	s_andn2_b64 vcc, exec, s[0:1]
	s_mov_b64 s[0:1], -1
	v_pk_mul_f32 v[8:9], v[136:137], v[8:9] op_sel_hi:[0,1]
	v_pk_mul_f32 v[0:1], v[136:137], v[0:1] op_sel_hi:[0,1]
	v_pk_mul_f32 v[10:11], v[136:137], v[10:11] op_sel_hi:[0,1]
	v_pk_mul_f32 v[2:3], v[136:137], v[2:3] op_sel_hi:[0,1]
	v_pk_mul_f32 v[246:247], v[8:9], v[240:241]
	v_pk_mul_f32 v[248:249], v[10:11], v[240:241]
	v_exp_f32_e32 v246, v246
	v_exp_f32_e32 v247, v247
	v_exp_f32_e32 v248, v248
	v_exp_f32_e32 v249, v249
	v_pk_add_f32 v[246:247], v[246:247], v[242:243]
	v_pk_add_f32 v[248:249], v[248:249], v[242:243]
	v_rcp_f32_e32 v246, v246
	v_rcp_f32_e32 v247, v247
	v_rcp_f32_e32 v248, v248
	v_rcp_f32_e32 v249, v249
	v_pk_mul_f32 v[8:9], v[8:9], v[246:247]
	v_pk_mul_f32 v[10:11], v[10:11], v[248:249]
	v_pk_mul_f32 v[8:9], v[8:9], v[0:1]
	v_pk_mul_f32 v[10:11], v[10:11], v[2:3]
	v_cvt_pk_bf16_f32 v0, v12, v13
	v_cvt_pk_bf16_f32 v1, v14, v15
	v_cvt_pk_bf16_f32 v2, v8, v9
	v_cvt_pk_bf16_f32 v3, v10, v11
	global_store_dwordx4 v[16:17], v[0:3], off
	s_cbranch_vccnz .LBB0_98
	s_nop 0
	v_lshl_add_u32 v0, s54, 8, v137
	v_ashrrev_i32_e32 v1, 31, v0
	v_lshl_add_u64 v[0:1], v[0:1], 2, s[16:17]
	global_load_dword v158, v[0:1], off
	global_load_dword v156, v[0:1], off offset:64
	global_load_dword v154, v[0:1], off offset:128
	global_load_dword v152, v[0:1], off offset:192
	global_load_dword v150, v[0:1], off offset:512
	global_load_dword v148, v[0:1], off offset:576
	global_load_dword v146, v[0:1], off offset:640
	global_load_dword v136, v[0:1], off offset:704
	s_andn2_b64 vcc, exec, s[6:7]
	s_cbranch_vccnz .LBB0_97
	s_barrier
	s_branch .LBB0_97

; #define PG8_STAGE(bufoff, gbase, voff) do { _Pragma("unroll") for (int _i = 0; _i < 2; ++_i) \
;         __builtin_amdgcn_global_load_lds((const unsigned*)((const char*)(gbase) + (voff)[_i]), (PG8_LAS unsigned*)(lds + (bufoff) + ldsw + _i * 8192), 16, 0, 0); } while (0)
; #define PG8_LDA(dst, b, h) do { _Pragma("unroll") for (int m = 0; m < 4; ++m) _Pragma("unroll") for (int k = 0; k < 2; ++k) dst[m][k] = *(const PG8_LAS bf16x8*)(lds + PG8_SA(b, h) + aoff + m * 2048 + k * 1024); } while (0)
; #define PG8_LDB(dst, b, h) do { _Pragma("unroll") for (int n = 0; n < 2; ++n) _Pragma("unroll") for (int k = 0; k < 2; ++k) dst[n][k] = *(const PG8_LAS bf16x8*)(lds + PG8_SB(b, h) + boff + n * 2048 + k * 1024); } while (0)
; template <class Epi, class Sched, bool ALIGN_EPI = false, bool SP2 = false>
; __device__ __forceinline__ void gemm_phase(PG8_LAS unsigned char* lds, const Gemm g, const Sched& S, const Epi& E) {
;     ...
;         for (int t = 0; t < nt; t += 2) {
;             const bool last = (t == nt - 2);
;             const char* a1 = cA + (size_t)(t + 1) * kstep;
;             const char* a2 = last ? nA : cA + (size_t)(t + 2) * kstep; const char* b2 = last ? nB : cB + (size_t)(t + 2) * kstep;
;             const char* a3 = a2 + kstep; const char* b3 = b2 + kstep;
;             if (last && has_next) S.a_ready(nxt);
;             if constexpr (SP2) {
;             PG8_LDB(B0, 0, 0); PG8_LDB(B1, 0, 1); PG8_SCHED; PG8_LDA(At, 0, 0); PG8_STAGE(PG8_SA(1, 1), a1 + hstep, voffA);
;             PG8_WAIT_V(8); PG8_WAIT_L(0); PG8_BAR; PG8_MMA(0, 0, At, B0); PG8_MMA(0, 1, At, B1); PG8_BAR; PG8_SCHED;
;             PG8_LDA(At, 0, 1); PG8_STAGE(PG8_SB(0, 0), b2, voffB); PG8_STAGE(PG8_SB(0, 1), b2 + hstep, voffB); PG8_STAGE(PG8_SA(0, 0), a2, voffA);
;             PG8_WAIT_V(8); PG8_WAIT_L(0); PG8_BAR; PG8_MMA(1, 0, At, B0); PG8_MMA(1, 1, At, B1); PG8_BAR; PG8_SCHED;
;             PG8_LDB(B0, 1, 0); PG8_LDB(B1, 1, 1); PG8_SCHED; PG8_LDA(At, 1, 0); PG8_STAGE(PG8_SA(0, 1), a2 + hstep, voffA);
;             PG8_WAIT_V(8); PG8_WAIT_L(0); PG8_BAR; PG8_MMA(0, 0, At, B0); PG8_MMA(0, 1, At, B1); PG8_BAR; PG8_SCHED;
;             PG8_LDA(At, 1, 1); PG8_STAGE(PG8_SB(1, 0), b3, voffB); PG8_STAGE(PG8_SB(1, 1), b3 + hstep, voffB); PG8_STAGE(PG8_SA(1, 0), a3, voffA);
;             PG8_WAIT_V(8); PG8_WAIT_L(0); PG8_BAR; PG8_MMA(1, 0, At, B0); PG8_MMA(1, 1, At, B1); PG8_BAR; PG8_SCHED;
.LBB0_700:
	ds_read_b128 v[164:167], v155
	ds_read_b128 v[168:171], v155 offset:1024
	ds_read_b128 v[172:175], v155 offset:2048
	ds_read_b128 v[176:179], v155 offset:3072
	ds_read_b128 v[180:183], v157
	ds_read_b128 v[184:187], v157 offset:1024
	ds_read_b128 v[188:191], v157 offset:2048
	ds_read_b128 v[192:195], v157 offset:3072
	s_add_u32 s46, s44, 0xfff80080
	s_addc_u32 s47, s45, -1
	s_cmp_eq_u32 s67, 28
	s_cselect_b32 s49, s10, s47
	s_cselect_b32 s48, s11, s46
	s_cselect_b32 s47, s21, s66
	s_cselect_b32 s46, s37, s65
	v_lshl_add_u64 v[228:229], s[44:45], 0, v[138:139]
	s_add_i32 m0, s43, 0xc000
	ds_read_b128 v[196:199], v159
	ds_read_b128 v[200:203], v159 offset:1024
	ds_read_b128 v[204:207], v159 offset:2048
	ds_read_b128 v[208:211], v159 offset:3072
	ds_read_b128 v[212:215], v159 offset:4096
	ds_read_b128 v[216:219], v159 offset:5120
	ds_read_b128 v[220:223], v159 offset:6144
	ds_read_b128 v[224:227], v159 offset:7168
	global_load_lds_dwordx4 v[228:229], off
	v_lshl_add_u64 v[228:229], s[44:45], 0, v[140:141]
	s_add_i32 m0, s43, 0xe000
	s_nop 0
	global_load_lds_dwordx4 v[228:229], off
	s_waitcnt vmcnt(8)
	s_waitcnt lgkmcnt(0)
	s_setprio 1
	s_barrier
	v_mfma_f32_16x16x32_bf16 v[124:127], v[164:167], v[196:199], v[124:127]
	v_mfma_f32_16x16x32_bf16 v[124:127], v[168:171], v[200:203], v[124:127]
	v_mfma_f32_16x16x32_bf16 v[108:111], v[164:167], v[204:207], v[108:111]
	v_mfma_f32_16x16x32_bf16 v[108:111], v[168:171], v[208:211], v[108:111]
	v_mfma_f32_16x16x32_bf16 v[92:95], v[164:167], v[212:215], v[92:95]
	v_mfma_f32_16x16x32_bf16 v[92:95], v[168:171], v[216:219], v[92:95]
	v_mfma_f32_16x16x32_bf16 v[76:79], v[164:167], v[220:223], v[76:79]
	v_mfma_f32_16x16x32_bf16 v[76:79], v[168:171], v[224:227], v[76:79]
	v_mfma_f32_16x16x32_bf16 v[72:75], v[172:175], v[220:223], v[72:75]
	v_mfma_f32_16x16x32_bf16 v[72:75], v[176:179], v[224:227], v[72:75]
	v_mfma_f32_16x16x32_bf16 v[88:91], v[172:175], v[212:215], v[88:91]
	v_mfma_f32_16x16x32_bf16 v[88:91], v[176:179], v[216:219], v[88:91]
	v_mfma_f32_16x16x32_bf16 v[104:107], v[172:175], v[204:207], v[104:107]
	v_mfma_f32_16x16x32_bf16 v[104:107], v[176:179], v[208:211], v[104:107]
	v_mfma_f32_16x16x32_bf16 v[120:123], v[172:175], v[196:199], v[120:123]
	v_mfma_f32_16x16x32_bf16 v[120:123], v[176:179], v[200:203], v[120:123]
	v_mfma_f32_16x16x32_bf16 v[116:119], v[180:183], v[196:199], v[116:119]
	v_mfma_f32_16x16x32_bf16 v[116:119], v[184:187], v[200:203], v[116:119]
	v_mfma_f32_16x16x32_bf16 v[100:103], v[180:183], v[204:207], v[100:103]
	v_mfma_f32_16x16x32_bf16 v[100:103], v[184:187], v[208:211], v[100:103]
	v_mfma_f32_16x16x32_bf16 v[84:87], v[180:183], v[212:215], v[84:87]
	v_mfma_f32_16x16x32_bf16 v[84:87], v[184:187], v[216:219], v[84:87]
	v_mfma_f32_16x16x32_bf16 v[68:71], v[180:183], v[220:223], v[68:71]
	v_mfma_f32_16x16x32_bf16 v[68:71], v[184:187], v[224:227], v[68:71]
	v_mfma_f32_16x16x32_bf16 v[64:67], v[188:191], v[220:223], v[64:67]
	v_mfma_f32_16x16x32_bf16 v[64:67], v[192:195], v[224:227], v[64:67]
	v_mfma_f32_16x16x32_bf16 v[80:83], v[188:191], v[212:215], v[80:83]
	v_mfma_f32_16x16x32_bf16 v[80:83], v[192:195], v[216:219], v[80:83]
	s_setprio 2
	s_barrier
	v_mfma_f32_16x16x32_bf16 v[96:99], v[188:191], v[204:207], v[96:99]
	v_mfma_f32_16x16x32_bf16 v[96:99], v[192:195], v[208:211], v[96:99]
	v_mfma_f32_16x16x32_bf16 v[112:115], v[188:191], v[196:199], v[112:115]
	v_mfma_f32_16x16x32_bf16 v[112:115], v[192:195], v[200:203], v[112:115]
	s_setprio 0
	s_add_i32 s62, s58, s3
	v_lshl_add_u64 v[228:229], s[46:47], 0, v[130:131]
	s_mov_b32 m0, s62
	ds_read_b128 v[196:199], v159 offset:16384
	ds_read_b128 v[200:203], v159 offset:17408
	ds_read_b128 v[204:207], v159 offset:18432
	ds_read_b128 v[208:211], v159 offset:19456
	ds_read_b128 v[212:215], v159 offset:20480
	ds_read_b128 v[216:219], v159 offset:21504
	ds_read_b128 v[220:223], v159 offset:22528
	ds_read_b128 v[224:227], v159 offset:23552
	global_load_lds_dwordx4 v[228:229], off
	s_add_i32 m0, s62, 0x2000
	s_add_u32 s62, s46, 0x80000
	v_lshl_add_u64 v[230:231], s[46:47], 0, v[134:135]
	s_addc_u32 s63, s47, 0
	s_add_i32 s68, s59, s3
	global_load_lds_dwordx4 v[230:231], off
	v_lshl_add_u64 v[232:233], s[62:63], 0, v[130:131]
	s_mov_b32 m0, s68
	v_lshl_add_u64 v[234:235], s[48:49], 0, v[132:133]
	global_load_lds_dwordx4 v[232:233], off
	v_lshl_add_u64 v[232:233], s[62:63], 0, v[134:135]
	s_add_i32 m0, s68, 0x2000
	s_nop 0
	global_load_lds_dwordx4 v[232:233], off
	v_lshl_add_u64 v[232:233], s[48:49], 0, v[128:129]
	s_mov_b32 m0, s43
	s_nop 0
	global_load_lds_dwordx4 v[232:233], off
	s_mov_b32 m0, s50
	s_nop 0
	global_load_lds_dwordx4 v[234:235], off
	s_waitcnt vmcnt(8)
	s_waitcnt lgkmcnt(0)
	s_setprio 1
	s_barrier
; #define PG8_STAGE(bufoff, gbase, voff) do { _Pragma("unroll") for (int _i = 0; _i < 2; ++_i) \
;         __builtin_amdgcn_global_load_lds((const unsigned*)((const char*)(gbase) + (voff)[_i]), (PG8_LAS unsigned*)(lds + (bufoff) + ldsw + _i * 8192), 16, 0, 0); } while (0)
; #define PG8_LDA(dst, b, h) do { _Pragma("unroll") for (int m = 0; m < 4; ++m) _Pragma("unroll") for (int k = 0; k < 2; ++k) dst[m][k] = *(const PG8_LAS bf16x8*)(lds + PG8_SA(b, h) + aoff + m * 2048 + k * 1024); } while (0)
; #define PG8_LDB(dst, b, h) do { _Pragma("unroll") for (int n = 0; n < 2; ++n) _Pragma("unroll") for (int k = 0; k < 2; ++k) dst[n][k] = *(const PG8_LAS bf16x8*)(lds + PG8_SB(b, h) + boff + n * 2048 + k * 1024); } while (0)
; #define PG8_MMA(ai, bj, At, Bt) do { __builtin_amdgcn_s_setprio(1); _Pragma("unroll") for (int m = 0; m < 4; ++m) _Pragma("unroll") for (int n = 0; n < 2; ++n) _Pragma("unroll") for (int k = 0; k < 2; ++k) \
;         acc[ai][bj][m][n] = __builtin_amdgcn_mfma_f32_16x16x32_bf16(Bt[n][k], At[m][k], acc[ai][bj][m][n], 0, 0, 0); __builtin_amdgcn_s_setprio(0); } while (0)
; #define PG8_WAIT_V(n) asm volatile("s_waitcnt vmcnt(" #n ")" ::: "memory")
; template <class Epi, class Sched, bool ALIGN_EPI = false, bool SP2 = false>
; __device__ __forceinline__ void gemm_phase(PG8_LAS unsigned char* lds, const Gemm g, const Sched& S, const Epi& E) {
;     ...
;             PG8_LDB(B0, 0, 0); PG8_LDB(B1, 0, 1); PG8_SCHED; PG8_LDA(At, 0, 0); PG8_STAGE(PG8_SA(1, 1), a1 + hstep, voffA);
;             PG8_WAIT_V(8); PG8_WAIT_L(0); PG8_BAR; PG8_MMA(0, 0, At, B0); PG8_MMA(0, 1, At, B1); PG8_BAR; PG8_SCHED;
;             PG8_LDA(At, 0, 1); PG8_STAGE(PG8_SB(0, 0), b2, voffB); PG8_STAGE(PG8_SB(0, 1), b2 + hstep, voffB); PG8_STAGE(PG8_SA(0, 0), a2, voffA);
;             PG8_WAIT_V(8); PG8_WAIT_L(0); PG8_BAR; PG8_MMA(1, 0, At, B0); PG8_MMA(1, 1, At, B1); PG8_BAR; PG8_SCHED;
;             PG8_LDB(B0, 1, 0); PG8_LDB(B1, 1, 1); PG8_SCHED; PG8_LDA(At, 1, 0); PG8_STAGE(PG8_SA(0, 1), a2 + hstep, voffA);
;             PG8_WAIT_V(8); PG8_WAIT_L(0); PG8_BAR; PG8_MMA(0, 0, At, B0); PG8_MMA(0, 1, At, B1); PG8_BAR; PG8_SCHED;
;             PG8_LDA(At, 1, 1); PG8_STAGE(PG8_SB(1, 0), b3, voffB); PG8_STAGE(PG8_SB(1, 1), b3 + hstep, voffB); PG8_STAGE(PG8_SA(1, 0), a3, voffA);
;             PG8_WAIT_V(8); PG8_WAIT_L(0); PG8_BAR; PG8_MMA(1, 0, At, B0); PG8_MMA(1, 1, At, B1); PG8_BAR; PG8_SCHED;
	v_mfma_f32_16x16x32_bf16 v[60:63], v[164:167], v[196:199], v[60:63]
	v_mfma_f32_16x16x32_bf16 v[60:63], v[168:171], v[200:203], v[60:63]
	v_mfma_f32_16x16x32_bf16 v[44:47], v[164:167], v[204:207], v[44:47]
	v_mfma_f32_16x16x32_bf16 v[44:47], v[168:171], v[208:211], v[44:47]
	v_mfma_f32_16x16x32_bf16 v[28:31], v[164:167], v[212:215], v[28:31]
	v_mfma_f32_16x16x32_bf16 v[28:31], v[168:171], v[216:219], v[28:31]
	v_mfma_f32_16x16x32_bf16 v[12:15], v[164:167], v[220:223], v[12:15]
	v_mfma_f32_16x16x32_bf16 v[12:15], v[168:171], v[224:227], v[12:15]
	v_mfma_f32_16x16x32_bf16 v[8:11], v[172:175], v[220:223], v[8:11]
	v_mfma_f32_16x16x32_bf16 v[8:11], v[176:179], v[224:227], v[8:11]
	v_mfma_f32_16x16x32_bf16 v[24:27], v[172:175], v[212:215], v[24:27]
	v_mfma_f32_16x16x32_bf16 v[24:27], v[176:179], v[216:219], v[24:27]
	v_mfma_f32_16x16x32_bf16 v[40:43], v[172:175], v[204:207], v[40:43]
	v_mfma_f32_16x16x32_bf16 v[40:43], v[176:179], v[208:211], v[40:43]
	v_mfma_f32_16x16x32_bf16 v[56:59], v[172:175], v[196:199], v[56:59]
	v_mfma_f32_16x16x32_bf16 v[56:59], v[176:179], v[200:203], v[56:59]
	v_mfma_f32_16x16x32_bf16 v[52:55], v[180:183], v[196:199], v[52:55]
	v_mfma_f32_16x16x32_bf16 v[52:55], v[184:187], v[200:203], v[52:55]
	v_mfma_f32_16x16x32_bf16 v[36:39], v[180:183], v[204:207], v[36:39]
	v_mfma_f32_16x16x32_bf16 v[36:39], v[184:187], v[208:211], v[36:39]
	v_mfma_f32_16x16x32_bf16 v[20:23], v[180:183], v[212:215], v[20:23]
	v_mfma_f32_16x16x32_bf16 v[20:23], v[184:187], v[216:219], v[20:23]
	v_mfma_f32_16x16x32_bf16 v[4:7], v[180:183], v[220:223], v[4:7]
	v_mfma_f32_16x16x32_bf16 v[4:7], v[184:187], v[224:227], v[4:7]
	v_mfma_f32_16x16x32_bf16 v[0:3], v[188:191], v[220:223], v[0:3]
	v_mfma_f32_16x16x32_bf16 v[0:3], v[192:195], v[224:227], v[0:3]
	v_mfma_f32_16x16x32_bf16 v[16:19], v[188:191], v[212:215], v[16:19]
	v_mfma_f32_16x16x32_bf16 v[16:19], v[192:195], v[216:219], v[16:19]
	s_setprio 2
	s_barrier
	v_mfma_f32_16x16x32_bf16 v[32:35], v[188:191], v[204:207], v[32:35]
	v_mfma_f32_16x16x32_bf16 v[32:35], v[192:195], v[208:211], v[32:35]
	v_mfma_f32_16x16x32_bf16 v[48:51], v[188:191], v[196:199], v[48:51]
	v_mfma_f32_16x16x32_bf16 v[48:51], v[192:195], v[200:203], v[48:51]
	s_setprio 0
	s_add_i32 s62, 0, 0x18000
	v_add_u32_e32 v161, s62, v147
	s_add_i32 s63, 0, 0x1c000
	ds_read_b128 v[164:167], v161
	ds_read_b128 v[168:171], v161 offset:1024
	ds_read_b128 v[172:175], v161 offset:2048
	ds_read_b128 v[176:179], v161 offset:3072
	v_add_u32_e32 v161, s63, v147
	ds_read_b128 v[180:183], v161
	ds_read_b128 v[184:187], v161 offset:1024
	ds_read_b128 v[188:191], v161 offset:2048
	ds_read_b128 v[192:195], v161 offset:3072
	s_add_u32 s48, s48, 0x80000
	s_addc_u32 s49, s49, 0
	s_mov_b32 m0, s51
	v_lshl_add_u64 v[236:237], s[48:49], 0, v[128:129]
	ds_read_b128 v[196:199], v159 offset:32768
	ds_read_b128 v[200:203], v159 offset:33792
	ds_read_b128 v[204:207], v159 offset:34816
	ds_read_b128 v[208:211], v159 offset:35840
	ds_read_b128 v[212:215], v159 offset:36864
	ds_read_b128 v[216:219], v159 offset:37888
	ds_read_b128 v[220:223], v159 offset:38912
	ds_read_b128 v[224:227], v159 offset:39936
	global_load_lds_dwordx4 v[236:237], off
	v_lshl_add_u64 v[236:237], s[48:49], 0, v[132:133]
	s_mov_b32 m0, s52
	s_nop 0
	global_load_lds_dwordx4 v[236:237], off
	s_waitcnt vmcnt(8)
	s_waitcnt lgkmcnt(0)
	s_setprio 1
	s_barrier
	v_mfma_f32_16x16x32_bf16 v[124:127], v[164:167], v[196:199], v[124:127]
	v_mfma_f32_16x16x32_bf16 v[124:127], v[168:171], v[200:203], v[124:127]
	v_mfma_f32_16x16x32_bf16 v[108:111], v[164:167], v[204:207], v[108:111]
	v_mfma_f32_16x16x32_bf16 v[108:111], v[168:171], v[208:211], v[108:111]
	v_mfma_f32_16x16x32_bf16 v[92:95], v[164:167], v[212:215], v[92:95]
	v_mfma_f32_16x16x32_bf16 v[92:95], v[168:171], v[216:219], v[92:95]
	v_mfma_f32_16x16x32_bf16 v[76:79], v[164:167], v[220:223], v[76:79]
	v_mfma_f32_16x16x32_bf16 v[76:79], v[168:171], v[224:227], v[76:79]
	v_mfma_f32_16x16x32_bf16 v[72:75], v[172:175], v[220:223], v[72:75]
	v_mfma_f32_16x16x32_bf16 v[72:75], v[176:179], v[224:227], v[72:75]
	v_mfma_f32_16x16x32_bf16 v[88:91], v[172:175], v[212:215], v[88:91]
	v_mfma_f32_16x16x32_bf16 v[88:91], v[176:179], v[216:219], v[88:91]
	v_mfma_f32_16x16x32_bf16 v[104:107], v[172:175], v[204:207], v[104:107]
	v_mfma_f32_16x16x32_bf16 v[104:107], v[176:179], v[208:211], v[104:107]
	v_mfma_f32_16x16x32_bf16 v[120:123], v[172:175], v[196:199], v[120:123]
	v_mfma_f32_16x16x32_bf16 v[120:123], v[176:179], v[200:203], v[120:123]
	v_mfma_f32_16x16x32_bf16 v[116:119], v[180:183], v[196:199], v[116:119]
	v_mfma_f32_16x16x32_bf16 v[116:119], v[184:187], v[200:203], v[116:119]
	v_mfma_f32_16x16x32_bf16 v[100:103], v[180:183], v[204:207], v[100:103]
	v_mfma_f32_16x16x32_bf16 v[100:103], v[184:187], v[208:211], v[100:103]
	v_mfma_f32_16x16x32_bf16 v[84:87], v[180:183], v[212:215], v[84:87]
	v_mfma_f32_16x16x32_bf16 v[84:87], v[184:187], v[216:219], v[84:87]
	v_mfma_f32_16x16x32_bf16 v[68:71], v[180:183], v[220:223], v[68:71]
	v_mfma_f32_16x16x32_bf16 v[68:71], v[184:187], v[224:227], v[68:71]
	v_mfma_f32_16x16x32_bf16 v[64:67], v[188:191], v[220:223], v[64:67]
	v_mfma_f32_16x16x32_bf16 v[64:67], v[192:195], v[224:227], v[64:67]
	v_mfma_f32_16x16x32_bf16 v[80:83], v[188:191], v[212:215], v[80:83]
	v_mfma_f32_16x16x32_bf16 v[80:83], v[192:195], v[216:219], v[80:83]
	s_setprio 2
	s_barrier
; #define PG8_STAGE(bufoff, gbase, voff) do { _Pragma("unroll") for (int _i = 0; _i < 2; ++_i) \
;         __builtin_amdgcn_global_load_lds((const unsigned*)((const char*)(gbase) + (voff)[_i]), (PG8_LAS unsigned*)(lds + (bufoff) + ldsw + _i * 8192), 16, 0, 0); } while (0)
; #define PG8_LDA(dst, b, h) do { _Pragma("unroll") for (int m = 0; m < 4; ++m) _Pragma("unroll") for (int k = 0; k < 2; ++k) dst[m][k] = *(const PG8_LAS bf16x8*)(lds + PG8_SA(b, h) + aoff + m * 2048 + k * 1024); } while (0)
; #define PG8_LDB(dst, b, h) do { _Pragma("unroll") for (int n = 0; n < 2; ++n) _Pragma("unroll") for (int k = 0; k < 2; ++k) dst[n][k] = *(const PG8_LAS bf16x8*)(lds + PG8_SB(b, h) + boff + n * 2048 + k * 1024); } while (0)
; template <class Epi, class Sched, bool ALIGN_EPI = false, bool SP2 = false>
; __device__ __forceinline__ void gemm_phase(PG8_LAS unsigned char* lds, const Gemm g, const Sched& S, const Epi& E) {
;     ...
;         for (int t = 0; t < nt; t += 2) {
;             const bool last = (t == nt - 2);
;             const char* a1 = cA + (size_t)(t + 1) * kstep;
;             const char* a2 = last ? nA : cA + (size_t)(t + 2) * kstep; const char* b2 = last ? nB : cB + (size_t)(t + 2) * kstep;
;             const char* a3 = a2 + kstep; const char* b3 = b2 + kstep;
;             if (last && has_next) S.a_ready(nxt);
;             if constexpr (SP2) {
;             PG8_LDB(B0, 0, 0); PG8_LDB(B1, 0, 1); PG8_SCHED; PG8_LDA(At, 0, 0); PG8_STAGE(PG8_SA(1, 1), a1 + hstep, voffA);
;             PG8_WAIT_V(8); PG8_WAIT_L(0); PG8_BAR; PG8_MMA(0, 0, At, B0); PG8_MMA(0, 1, At, B1); PG8_BAR; PG8_SCHED;
;             PG8_LDA(At, 0, 1); PG8_STAGE(PG8_SB(0, 0), b2, voffB); PG8_STAGE(PG8_SB(0, 1), b2 + hstep, voffB); PG8_STAGE(PG8_SA(0, 0), a2, voffA);
;             PG8_WAIT_V(8); PG8_WAIT_L(0); PG8_BAR; PG8_MMA(1, 0, At, B0); PG8_MMA(1, 1, At, B1); PG8_BAR; PG8_SCHED;
;             PG8_LDB(B0, 1, 0); PG8_LDB(B1, 1, 1); PG8_SCHED; PG8_LDA(At, 1, 0); PG8_STAGE(PG8_SA(0, 1), a2 + hstep, voffA);
;             PG8_WAIT_V(8); PG8_WAIT_L(0); PG8_BAR; PG8_MMA(0, 0, At, B0); PG8_MMA(0, 1, At, B1); PG8_BAR; PG8_SCHED;
;             PG8_LDA(At, 1, 1); PG8_STAGE(PG8_SB(1, 0), b3, voffB); PG8_STAGE(PG8_SB(1, 1), b3 + hstep, voffB); PG8_STAGE(PG8_SA(1, 0), a3, voffA);
;             PG8_WAIT_V(8); PG8_WAIT_L(0); PG8_BAR; PG8_MMA(1, 0, At, B0); PG8_MMA(1, 1, At, B1); PG8_BAR; PG8_SCHED;
	v_mfma_f32_16x16x32_bf16 v[96:99], v[188:191], v[204:207], v[96:99]
	v_mfma_f32_16x16x32_bf16 v[96:99], v[192:195], v[208:211], v[96:99]
	v_mfma_f32_16x16x32_bf16 v[112:115], v[188:191], v[196:199], v[112:115]
	v_mfma_f32_16x16x32_bf16 v[112:115], v[192:195], v[200:203], v[112:115]
	s_setprio 0
	s_add_i32 s48, s62, s3
	v_lshl_add_u64 v[228:229], v[228:229], 0, s[8:9]
	s_mov_b32 m0, s48
	ds_read_b128 v[196:199], v159 offset:49152
	ds_read_b128 v[200:203], v159 offset:50176
	ds_read_b128 v[204:207], v159 offset:51200
	ds_read_b128 v[208:211], v159 offset:52224
	ds_read_b128 v[212:215], v159 offset:53248
	ds_read_b128 v[216:219], v159 offset:54272
	ds_read_b128 v[220:223], v159 offset:55296
	ds_read_b128 v[224:227], v159 offset:56320
	global_load_lds_dwordx4 v[228:229], off
	s_add_i32 m0, s48, 0x2000
	s_add_u32 s46, s46, 0x80080
	v_lshl_add_u64 v[228:229], v[230:231], 0, s[8:9]
	s_addc_u32 s47, s47, 0
	s_add_i32 s48, s63, s3
	global_load_lds_dwordx4 v[228:229], off
	v_lshl_add_u64 v[228:229], s[46:47], 0, v[130:131]
	s_mov_b32 m0, s48
	s_nop 0
	global_load_lds_dwordx4 v[228:229], off
	v_lshl_add_u64 v[228:229], s[46:47], 0, v[134:135]
	s_add_i32 m0, s48, 0x2000
	s_nop 0
	global_load_lds_dwordx4 v[228:229], off
	v_lshl_add_u64 v[228:229], v[232:233], 0, s[8:9]
	s_mov_b32 m0, s55
	s_nop 0
	global_load_lds_dwordx4 v[228:229], off
	v_lshl_add_u64 v[228:229], v[234:235], 0, s[8:9]
	s_mov_b32 m0, s56
	s_nop 0
	global_load_lds_dwordx4 v[228:229], off
	s_waitcnt vmcnt(8)
	s_waitcnt lgkmcnt(0)
	s_setprio 1
	s_barrier
	v_mfma_f32_16x16x32_bf16 v[60:63], v[164:167], v[196:199], v[60:63]
	v_mfma_f32_16x16x32_bf16 v[60:63], v[168:171], v[200:203], v[60:63]
	v_mfma_f32_16x16x32_bf16 v[44:47], v[164:167], v[204:207], v[44:47]
	v_mfma_f32_16x16x32_bf16 v[44:47], v[168:171], v[208:211], v[44:47]
	v_mfma_f32_16x16x32_bf16 v[28:31], v[164:167], v[212:215], v[28:31]
	v_mfma_f32_16x16x32_bf16 v[28:31], v[168:171], v[216:219], v[28:31]
	v_mfma_f32_16x16x32_bf16 v[12:15], v[164:167], v[220:223], v[12:15]
	v_mfma_f32_16x16x32_bf16 v[12:15], v[168:171], v[224:227], v[12:15]
	v_mfma_f32_16x16x32_bf16 v[8:11], v[172:175], v[220:223], v[8:11]
	v_mfma_f32_16x16x32_bf16 v[8:11], v[176:179], v[224:227], v[8:11]
	v_mfma_f32_16x16x32_bf16 v[24:27], v[172:175], v[212:215], v[24:27]
	v_mfma_f32_16x16x32_bf16 v[24:27], v[176:179], v[216:219], v[24:27]
	v_mfma_f32_16x16x32_bf16 v[40:43], v[172:175], v[204:207], v[40:43]
	v_mfma_f32_16x16x32_bf16 v[40:43], v[176:179], v[208:211], v[40:43]
	v_mfma_f32_16x16x32_bf16 v[56:59], v[172:175], v[196:199], v[56:59]
	v_mfma_f32_16x16x32_bf16 v[56:59], v[176:179], v[200:203], v[56:59]
	v_mfma_f32_16x16x32_bf16 v[52:55], v[180:183], v[196:199], v[52:55]
	v_mfma_f32_16x16x32_bf16 v[52:55], v[184:187], v[200:203], v[52:55]
	v_mfma_f32_16x16x32_bf16 v[36:39], v[180:183], v[204:207], v[36:39]
	v_mfma_f32_16x16x32_bf16 v[36:39], v[184:187], v[208:211], v[36:39]
	v_mfma_f32_16x16x32_bf16 v[20:23], v[180:183], v[212:215], v[20:23]
	v_mfma_f32_16x16x32_bf16 v[20:23], v[184:187], v[216:219], v[20:23]
	v_mfma_f32_16x16x32_bf16 v[4:7], v[180:183], v[220:223], v[4:7]
	v_mfma_f32_16x16x32_bf16 v[4:7], v[184:187], v[224:227], v[4:7]
	v_mfma_f32_16x16x32_bf16 v[0:3], v[188:191], v[220:223], v[0:3]
	v_mfma_f32_16x16x32_bf16 v[0:3], v[192:195], v[224:227], v[0:3]
	v_mfma_f32_16x16x32_bf16 v[16:19], v[188:191], v[212:215], v[16:19]
	v_mfma_f32_16x16x32_bf16 v[16:19], v[192:195], v[216:219], v[16:19]
	s_setprio 2
	s_barrier
	v_mfma_f32_16x16x32_bf16 v[32:35], v[188:191], v[204:207], v[32:35]
	v_mfma_f32_16x16x32_bf16 v[32:35], v[192:195], v[208:211], v[32:35]
	v_mfma_f32_16x16x32_bf16 v[48:51], v[188:191], v[196:199], v[48:51]
	v_mfma_f32_16x16x32_bf16 v[48:51], v[192:195], v[200:203], v[48:51]
	s_setprio 0
	s_add_i32 s67, s67, 2
	s_add_u32 s44, s44, 0x100
	s_addc_u32 s45, s45, 0
	s_add_u32 s65, s65, 0x100
	s_addc_u32 s66, s66, 0
	s_cmp_gt_u32 s67, 27
	s_cbranch_scc0 .LBB0_700
	ds_read_b128 v[164:167], v155
	ds_read_b128 v[168:171], v155 offset:1024
	ds_read_b128 v[172:175], v155 offset:2048
	ds_read_b128 v[176:179], v155 offset:3072
	ds_read_b128 v[180:183], v157
	ds_read_b128 v[184:187], v157 offset:1024
	ds_read_b128 v[188:191], v157 offset:2048
	ds_read_b128 v[192:195], v157 offset:3072
	s_add_u32 s46, s44, 0xfff80080
	s_addc_u32 s47, s45, -1
	s_cmp_eq_u32 s67, 28
	s_cselect_b32 s49, s10, s47
	s_cselect_b32 s48, s11, s46
	s_cselect_b32 s47, s21, s66
	s_cselect_b32 s46, s37, s65
	v_lshl_add_u64 v[228:229], s[44:45], 0, v[138:139]
	s_add_i32 m0, s43, 0xc000
	ds_read_b128 v[196:199], v159
	ds_read_b128 v[200:203], v159 offset:1024
	ds_read_b128 v[204:207], v159 offset:2048
	ds_read_b128 v[208:211], v159 offset:3072
	ds_read_b128 v[212:215], v159 offset:4096
	ds_read_b128 v[216:219], v159 offset:5120
	ds_read_b128 v[220:223], v159 offset:6144
	ds_read_b128 v[224:227], v159 offset:7168
	global_load_lds_dwordx4 v[228:229], off
	v_lshl_add_u64 v[228:229], s[44:45], 0, v[140:141]
	s_add_i32 m0, s43, 0xe000
	s_nop 0
	global_load_lds_dwordx4 v[228:229], off
	s_waitcnt vmcnt(8)
	s_waitcnt lgkmcnt(0)
	s_setprio 1
	s_barrier
; #define PG8_STAGE(bufoff, gbase, voff) do { _Pragma("unroll") for (int _i = 0; _i < 2; ++_i) \
;         __builtin_amdgcn_global_load_lds((const unsigned*)((const char*)(gbase) + (voff)[_i]), (PG8_LAS unsigned*)(lds + (bufoff) + ldsw + _i * 8192), 16, 0, 0); } while (0)
; #define PG8_LDA(dst, b, h) do { _Pragma("unroll") for (int m = 0; m < 4; ++m) _Pragma("unroll") for (int k = 0; k < 2; ++k) dst[m][k] = *(const PG8_LAS bf16x8*)(lds + PG8_SA(b, h) + aoff + m * 2048 + k * 1024); } while (0)
; #define PG8_LDB(dst, b, h) do { _Pragma("unroll") for (int n = 0; n < 2; ++n) _Pragma("unroll") for (int k = 0; k < 2; ++k) dst[n][k] = *(const PG8_LAS bf16x8*)(lds + PG8_SB(b, h) + boff + n * 2048 + k * 1024); } while (0)
; #define PG8_MMA(ai, bj, At, Bt) do { __builtin_amdgcn_s_setprio(1); _Pragma("unroll") for (int m = 0; m < 4; ++m) _Pragma("unroll") for (int n = 0; n < 2; ++n) _Pragma("unroll") for (int k = 0; k < 2; ++k) \
;         acc[ai][bj][m][n] = __builtin_amdgcn_mfma_f32_16x16x32_bf16(Bt[n][k], At[m][k], acc[ai][bj][m][n], 0, 0, 0); __builtin_amdgcn_s_setprio(0); } while (0)
; #define PG8_WAIT_V(n) asm volatile("s_waitcnt vmcnt(" #n ")" ::: "memory")
; template <class Epi, class Sched, bool ALIGN_EPI = false, bool SP2 = false>
; __device__ __forceinline__ void gemm_phase(PG8_LAS unsigned char* lds, const Gemm g, const Sched& S, const Epi& E) {
;     ...
;             PG8_LDB(B0, 0, 0); PG8_LDB(B1, 0, 1); PG8_SCHED; PG8_LDA(At, 0, 0); PG8_STAGE(PG8_SA(1, 1), a1 + hstep, voffA);
;             PG8_WAIT_V(8); PG8_WAIT_L(0); PG8_BAR; PG8_MMA(0, 0, At, B0); PG8_MMA(0, 1, At, B1); PG8_BAR; PG8_SCHED;
;             PG8_LDA(At, 0, 1); PG8_STAGE(PG8_SB(0, 0), b2, voffB); PG8_STAGE(PG8_SB(0, 1), b2 + hstep, voffB); PG8_STAGE(PG8_SA(0, 0), a2, voffA);
;             PG8_WAIT_V(8); PG8_WAIT_L(0); PG8_BAR; PG8_MMA(1, 0, At, B0); PG8_MMA(1, 1, At, B1); PG8_BAR; PG8_SCHED;
;             PG8_LDB(B0, 1, 0); PG8_LDB(B1, 1, 1); PG8_SCHED; PG8_LDA(At, 1, 0); PG8_STAGE(PG8_SA(0, 1), a2 + hstep, voffA);
;             PG8_WAIT_V(8); PG8_WAIT_L(0); PG8_BAR; PG8_MMA(0, 0, At, B0); PG8_MMA(0, 1, At, B1); PG8_BAR; PG8_SCHED;
;             PG8_LDA(At, 1, 1); PG8_STAGE(PG8_SB(1, 0), b3, voffB); PG8_STAGE(PG8_SB(1, 1), b3 + hstep, voffB); PG8_STAGE(PG8_SA(1, 0), a3, voffA);
;             PG8_WAIT_V(8); PG8_WAIT_L(0); PG8_BAR; PG8_MMA(1, 0, At, B0); PG8_MMA(1, 1, At, B1); PG8_BAR; PG8_SCHED;
	v_mfma_f32_16x16x32_bf16 v[124:127], v[164:167], v[196:199], v[124:127]
	v_mfma_f32_16x16x32_bf16 v[124:127], v[168:171], v[200:203], v[124:127]
	v_mfma_f32_16x16x32_bf16 v[108:111], v[164:167], v[204:207], v[108:111]
	v_mfma_f32_16x16x32_bf16 v[108:111], v[168:171], v[208:211], v[108:111]
	v_mfma_f32_16x16x32_bf16 v[92:95], v[164:167], v[212:215], v[92:95]
	v_mfma_f32_16x16x32_bf16 v[92:95], v[168:171], v[216:219], v[92:95]
	v_mfma_f32_16x16x32_bf16 v[76:79], v[164:167], v[220:223], v[76:79]
	v_mfma_f32_16x16x32_bf16 v[76:79], v[168:171], v[224:227], v[76:79]
	v_mfma_f32_16x16x32_bf16 v[72:75], v[172:175], v[220:223], v[72:75]
	v_mfma_f32_16x16x32_bf16 v[72:75], v[176:179], v[224:227], v[72:75]
	v_mfma_f32_16x16x32_bf16 v[88:91], v[172:175], v[212:215], v[88:91]
	v_mfma_f32_16x16x32_bf16 v[88:91], v[176:179], v[216:219], v[88:91]
	v_mfma_f32_16x16x32_bf16 v[104:107], v[172:175], v[204:207], v[104:107]
	v_mfma_f32_16x16x32_bf16 v[104:107], v[176:179], v[208:211], v[104:107]
	v_mfma_f32_16x16x32_bf16 v[120:123], v[172:175], v[196:199], v[120:123]
	v_mfma_f32_16x16x32_bf16 v[120:123], v[176:179], v[200:203], v[120:123]
	v_mfma_f32_16x16x32_bf16 v[116:119], v[180:183], v[196:199], v[116:119]
	v_mfma_f32_16x16x32_bf16 v[116:119], v[184:187], v[200:203], v[116:119]
	v_mfma_f32_16x16x32_bf16 v[100:103], v[180:183], v[204:207], v[100:103]
	v_mfma_f32_16x16x32_bf16 v[100:103], v[184:187], v[208:211], v[100:103]
	v_mfma_f32_16x16x32_bf16 v[84:87], v[180:183], v[212:215], v[84:87]
	v_mfma_f32_16x16x32_bf16 v[84:87], v[184:187], v[216:219], v[84:87]
	v_mfma_f32_16x16x32_bf16 v[68:71], v[180:183], v[220:223], v[68:71]
	v_mfma_f32_16x16x32_bf16 v[68:71], v[184:187], v[224:227], v[68:71]
	v_mfma_f32_16x16x32_bf16 v[64:67], v[188:191], v[220:223], v[64:67]
	v_mfma_f32_16x16x32_bf16 v[64:67], v[192:195], v[224:227], v[64:67]
	v_mfma_f32_16x16x32_bf16 v[80:83], v[188:191], v[212:215], v[80:83]
	v_mfma_f32_16x16x32_bf16 v[80:83], v[192:195], v[216:219], v[80:83]
	s_setprio 2
	s_barrier
	v_mfma_f32_16x16x32_bf16 v[96:99], v[188:191], v[204:207], v[96:99]
	v_mfma_f32_16x16x32_bf16 v[96:99], v[192:195], v[208:211], v[96:99]
	v_mfma_f32_16x16x32_bf16 v[112:115], v[188:191], v[196:199], v[112:115]
	v_mfma_f32_16x16x32_bf16 v[112:115], v[192:195], v[200:203], v[112:115]
	s_setprio 0
	s_add_i32 s62, s58, s3
	v_lshl_add_u64 v[228:229], s[46:47], 0, v[130:131]
	s_mov_b32 m0, s62
	ds_read_b128 v[196:199], v159 offset:16384
	ds_read_b128 v[200:203], v159 offset:17408
	ds_read_b128 v[204:207], v159 offset:18432
	ds_read_b128 v[208:211], v159 offset:19456
	ds_read_b128 v[212:215], v159 offset:20480
	ds_read_b128 v[216:219], v159 offset:21504
	ds_read_b128 v[220:223], v159 offset:22528
	ds_read_b128 v[224:227], v159 offset:23552
	global_load_lds_dwordx4 v[228:229], off
	s_add_i32 m0, s62, 0x2000
	s_add_u32 s62, s46, 0x80000
	v_lshl_add_u64 v[230:231], s[46:47], 0, v[134:135]
	s_addc_u32 s63, s47, 0
	s_add_i32 s68, s59, s3
	global_load_lds_dwordx4 v[230:231], off
	v_lshl_add_u64 v[232:233], s[62:63], 0, v[130:131]
	s_mov_b32 m0, s68
	v_lshl_add_u64 v[234:235], s[48:49], 0, v[132:133]
	global_load_lds_dwordx4 v[232:233], off
	v_lshl_add_u64 v[232:233], s[62:63], 0, v[134:135]
	s_add_i32 m0, s68, 0x2000
	s_nop 0
	global_load_lds_dwordx4 v[232:233], off
	v_lshl_add_u64 v[232:233], s[48:49], 0, v[128:129]
	s_mov_b32 m0, s43
	s_nop 0
	global_load_lds_dwordx4 v[232:233], off
	s_mov_b32 m0, s50
	s_nop 0
	global_load_lds_dwordx4 v[234:235], off
	s_waitcnt vmcnt(8)
	s_waitcnt lgkmcnt(0)
	s_setprio 1
	s_barrier
	v_mfma_f32_16x16x32_bf16 v[60:63], v[164:167], v[196:199], v[60:63]
	v_mfma_f32_16x16x32_bf16 v[60:63], v[168:171], v[200:203], v[60:63]
	v_mfma_f32_16x16x32_bf16 v[44:47], v[164:167], v[204:207], v[44:47]
	v_mfma_f32_16x16x32_bf16 v[44:47], v[168:171], v[208:211], v[44:47]
	v_mfma_f32_16x16x32_bf16 v[28:31], v[164:167], v[212:215], v[28:31]
	v_mfma_f32_16x16x32_bf16 v[28:31], v[168:171], v[216:219], v[28:31]
	v_mfma_f32_16x16x32_bf16 v[12:15], v[164:167], v[220:223], v[12:15]
	v_mfma_f32_16x16x32_bf16 v[12:15], v[168:171], v[224:227], v[12:15]
	v_mfma_f32_16x16x32_bf16 v[8:11], v[172:175], v[220:223], v[8:11]
	v_mfma_f32_16x16x32_bf16 v[8:11], v[176:179], v[224:227], v[8:11]
	v_mfma_f32_16x16x32_bf16 v[24:27], v[172:175], v[212:215], v[24:27]
	v_mfma_f32_16x16x32_bf16 v[24:27], v[176:179], v[216:219], v[24:27]
	v_mfma_f32_16x16x32_bf16 v[40:43], v[172:175], v[204:207], v[40:43]
	v_mfma_f32_16x16x32_bf16 v[40:43], v[176:179], v[208:211], v[40:43]
	v_mfma_f32_16x16x32_bf16 v[56:59], v[172:175], v[196:199], v[56:59]
	v_mfma_f32_16x16x32_bf16 v[56:59], v[176:179], v[200:203], v[56:59]
	v_mfma_f32_16x16x32_bf16 v[52:55], v[180:183], v[196:199], v[52:55]
	v_mfma_f32_16x16x32_bf16 v[52:55], v[184:187], v[200:203], v[52:55]
	v_mfma_f32_16x16x32_bf16 v[36:39], v[180:183], v[204:207], v[36:39]
	v_mfma_f32_16x16x32_bf16 v[36:39], v[184:187], v[208:211], v[36:39]
	v_mfma_f32_16x16x32_bf16 v[20:23], v[180:183], v[212:215], v[20:23]
	v_mfma_f32_16x16x32_bf16 v[20:23], v[184:187], v[216:219], v[20:23]
	v_mfma_f32_16x16x32_bf16 v[4:7], v[180:183], v[220:223], v[4:7]
	v_mfma_f32_16x16x32_bf16 v[4:7], v[184:187], v[224:227], v[4:7]
	v_mfma_f32_16x16x32_bf16 v[0:3], v[188:191], v[220:223], v[0:3]
	v_mfma_f32_16x16x32_bf16 v[0:3], v[192:195], v[224:227], v[0:3]
	v_mfma_f32_16x16x32_bf16 v[16:19], v[188:191], v[212:215], v[16:19]
	v_mfma_f32_16x16x32_bf16 v[16:19], v[192:195], v[216:219], v[16:19]
	s_setprio 2
	s_barrier
; #define PG8_STAGE(bufoff, gbase, voff) do { _Pragma("unroll") for (int _i = 0; _i < 2; ++_i) \
;         __builtin_amdgcn_global_load_lds((const unsigned*)((const char*)(gbase) + (voff)[_i]), (PG8_LAS unsigned*)(lds + (bufoff) + ldsw + _i * 8192), 16, 0, 0); } while (0)
; #define PG8_LDA(dst, b, h) do { _Pragma("unroll") for (int m = 0; m < 4; ++m) _Pragma("unroll") for (int k = 0; k < 2; ++k) dst[m][k] = *(const PG8_LAS bf16x8*)(lds + PG8_SA(b, h) + aoff + m * 2048 + k * 1024); } while (0)
; #define PG8_LDB(dst, b, h) do { _Pragma("unroll") for (int n = 0; n < 2; ++n) _Pragma("unroll") for (int k = 0; k < 2; ++k) dst[n][k] = *(const PG8_LAS bf16x8*)(lds + PG8_SB(b, h) + boff + n * 2048 + k * 1024); } while (0)
; #define PG8_MMA(ai, bj, At, Bt) do { __builtin_amdgcn_s_setprio(1); _Pragma("unroll") for (int m = 0; m < 4; ++m) _Pragma("unroll") for (int n = 0; n < 2; ++n) _Pragma("unroll") for (int k = 0; k < 2; ++k) \
;         acc[ai][bj][m][n] = __builtin_amdgcn_mfma_f32_16x16x32_bf16(Bt[n][k], At[m][k], acc[ai][bj][m][n], 0, 0, 0); __builtin_amdgcn_s_setprio(0); } while (0)
; #define PG8_WAIT_V(n) asm volatile("s_waitcnt vmcnt(" #n ")" ::: "memory")
; template <class Epi, class Sched, bool ALIGN_EPI = false, bool SP2 = false>
; __device__ __forceinline__ void gemm_phase(PG8_LAS unsigned char* lds, const Gemm g, const Sched& S, const Epi& E) {
;     ...
;             PG8_LDB(B0, 0, 0); PG8_LDB(B1, 0, 1); PG8_SCHED; PG8_LDA(At, 0, 0); PG8_STAGE(PG8_SA(1, 1), a1 + hstep, voffA);
;             PG8_WAIT_V(8); PG8_WAIT_L(0); PG8_BAR; PG8_MMA(0, 0, At, B0); PG8_MMA(0, 1, At, B1); PG8_BAR; PG8_SCHED;
;             PG8_LDA(At, 0, 1); PG8_STAGE(PG8_SB(0, 0), b2, voffB); PG8_STAGE(PG8_SB(0, 1), b2 + hstep, voffB); PG8_STAGE(PG8_SA(0, 0), a2, voffA);
;             PG8_WAIT_V(8); PG8_WAIT_L(0); PG8_BAR; PG8_MMA(1, 0, At, B0); PG8_MMA(1, 1, At, B1); PG8_BAR; PG8_SCHED;
;             PG8_LDB(B0, 1, 0); PG8_LDB(B1, 1, 1); PG8_SCHED; PG8_LDA(At, 1, 0); PG8_STAGE(PG8_SA(0, 1), a2 + hstep, voffA);
;             PG8_WAIT_V(8); PG8_WAIT_L(0); PG8_BAR; PG8_MMA(0, 0, At, B0); PG8_MMA(0, 1, At, B1); PG8_BAR; PG8_SCHED;
;             PG8_LDA(At, 1, 1); PG8_STAGE(PG8_SB(1, 0), b3, voffB); PG8_STAGE(PG8_SB(1, 1), b3 + hstep, voffB); PG8_STAGE(PG8_SA(1, 0), a3, voffA);
;             PG8_WAIT_V(8); PG8_WAIT_L(0); PG8_BAR; PG8_MMA(1, 0, At, B0); PG8_MMA(1, 1, At, B1); PG8_BAR; PG8_SCHED;
	v_mfma_f32_16x16x32_bf16 v[32:35], v[188:191], v[204:207], v[32:35]
	v_mfma_f32_16x16x32_bf16 v[32:35], v[192:195], v[208:211], v[32:35]
	v_mfma_f32_16x16x32_bf16 v[48:51], v[188:191], v[196:199], v[48:51]
	v_mfma_f32_16x16x32_bf16 v[48:51], v[192:195], v[200:203], v[48:51]
	s_setprio 0
	s_add_i32 s62, 0, 0x18000
	v_add_u32_e32 v161, s62, v147
	s_add_i32 s63, 0, 0x1c000
	ds_read_b128 v[164:167], v161
	ds_read_b128 v[168:171], v161 offset:1024
	ds_read_b128 v[172:175], v161 offset:2048
	ds_read_b128 v[176:179], v161 offset:3072
	v_add_u32_e32 v161, s63, v147
	ds_read_b128 v[180:183], v161
	ds_read_b128 v[184:187], v161 offset:1024
	ds_read_b128 v[188:191], v161 offset:2048
	ds_read_b128 v[192:195], v161 offset:3072
	s_add_u32 s48, s48, 0x80000
	s_addc_u32 s49, s49, 0
	s_mov_b32 m0, s51
	v_lshl_add_u64 v[236:237], s[48:49], 0, v[128:129]
	ds_read_b128 v[196:199], v159 offset:32768
	ds_read_b128 v[200:203], v159 offset:33792
	ds_read_b128 v[204:207], v159 offset:34816
	ds_read_b128 v[208:211], v159 offset:35840
	ds_read_b128 v[212:215], v159 offset:36864
	ds_read_b128 v[216:219], v159 offset:37888
	ds_read_b128 v[220:223], v159 offset:38912
	ds_read_b128 v[224:227], v159 offset:39936
	global_load_lds_dwordx4 v[236:237], off
	v_lshl_add_u64 v[236:237], s[48:49], 0, v[132:133]
	s_mov_b32 m0, s52
	s_nop 0
	global_load_lds_dwordx4 v[236:237], off
	s_waitcnt vmcnt(8)
	s_waitcnt lgkmcnt(0)
	s_setprio 1
	s_barrier
	v_mfma_f32_16x16x32_bf16 v[124:127], v[164:167], v[196:199], v[124:127]
	v_mfma_f32_16x16x32_bf16 v[124:127], v[168:171], v[200:203], v[124:127]
	v_mfma_f32_16x16x32_bf16 v[108:111], v[164:167], v[204:207], v[108:111]
	v_mfma_f32_16x16x32_bf16 v[108:111], v[168:171], v[208:211], v[108:111]
	v_mfma_f32_16x16x32_bf16 v[92:95], v[164:167], v[212:215], v[92:95]
	v_mfma_f32_16x16x32_bf16 v[92:95], v[168:171], v[216:219], v[92:95]
	v_mfma_f32_16x16x32_bf16 v[76:79], v[164:167], v[220:223], v[76:79]
	v_mfma_f32_16x16x32_bf16 v[76:79], v[168:171], v[224:227], v[76:79]
	v_mfma_f32_16x16x32_bf16 v[72:75], v[172:175], v[220:223], v[72:75]
	v_mfma_f32_16x16x32_bf16 v[72:75], v[176:179], v[224:227], v[72:75]
	v_mfma_f32_16x16x32_bf16 v[88:91], v[172:175], v[212:215], v[88:91]
	v_mfma_f32_16x16x32_bf16 v[88:91], v[176:179], v[216:219], v[88:91]
	v_mfma_f32_16x16x32_bf16 v[104:107], v[172:175], v[204:207], v[104:107]
	v_mfma_f32_16x16x32_bf16 v[104:107], v[176:179], v[208:211], v[104:107]
	v_mfma_f32_16x16x32_bf16 v[120:123], v[172:175], v[196:199], v[120:123]
	v_mfma_f32_16x16x32_bf16 v[120:123], v[176:179], v[200:203], v[120:123]
	v_mfma_f32_16x16x32_bf16 v[116:119], v[180:183], v[196:199], v[116:119]
	v_mfma_f32_16x16x32_bf16 v[116:119], v[184:187], v[200:203], v[116:119]
	v_mfma_f32_16x16x32_bf16 v[100:103], v[180:183], v[204:207], v[100:103]
	v_mfma_f32_16x16x32_bf16 v[100:103], v[184:187], v[208:211], v[100:103]
	v_mfma_f32_16x16x32_bf16 v[84:87], v[180:183], v[212:215], v[84:87]
	v_mfma_f32_16x16x32_bf16 v[84:87], v[184:187], v[216:219], v[84:87]
	v_mfma_f32_16x16x32_bf16 v[68:71], v[180:183], v[220:223], v[68:71]
	v_mfma_f32_16x16x32_bf16 v[68:71], v[184:187], v[224:227], v[68:71]
	v_mfma_f32_16x16x32_bf16 v[64:67], v[188:191], v[220:223], v[64:67]
	v_mfma_f32_16x16x32_bf16 v[64:67], v[192:195], v[224:227], v[64:67]
	v_mfma_f32_16x16x32_bf16 v[80:83], v[188:191], v[212:215], v[80:83]
	v_mfma_f32_16x16x32_bf16 v[80:83], v[192:195], v[216:219], v[80:83]
	s_setprio 2
	s_barrier
	v_mfma_f32_16x16x32_bf16 v[96:99], v[188:191], v[204:207], v[96:99]
	v_mfma_f32_16x16x32_bf16 v[96:99], v[192:195], v[208:211], v[96:99]
	v_mfma_f32_16x16x32_bf16 v[112:115], v[188:191], v[196:199], v[112:115]
	v_mfma_f32_16x16x32_bf16 v[112:115], v[192:195], v[200:203], v[112:115]
	s_setprio 0
	s_add_i32 s48, s62, s3
	v_lshl_add_u64 v[228:229], v[228:229], 0, s[8:9]
	s_mov_b32 m0, s48
	ds_read_b128 v[196:199], v159 offset:49152
	ds_read_b128 v[200:203], v159 offset:50176
	ds_read_b128 v[204:207], v159 offset:51200
	ds_read_b128 v[208:211], v159 offset:52224
	ds_read_b128 v[212:215], v159 offset:53248
	ds_read_b128 v[216:219], v159 offset:54272
	ds_read_b128 v[220:223], v159 offset:55296
	ds_read_b128 v[224:227], v159 offset:56320
	global_load_lds_dwordx4 v[228:229], off
	s_add_i32 m0, s48, 0x2000
	s_add_u32 s46, s46, 0x80080
	v_lshl_add_u64 v[228:229], v[230:231], 0, s[8:9]
	s_addc_u32 s47, s47, 0
	s_add_i32 s48, s63, s3
	global_load_lds_dwordx4 v[228:229], off
	v_lshl_add_u64 v[228:229], s[46:47], 0, v[130:131]
	s_mov_b32 m0, s48
	s_nop 0
	global_load_lds_dwordx4 v[228:229], off
	v_lshl_add_u64 v[228:229], s[46:47], 0, v[134:135]
	s_add_i32 m0, s48, 0x2000
	s_nop 0
	global_load_lds_dwordx4 v[228:229], off
	v_lshl_add_u64 v[228:229], v[232:233], 0, s[8:9]
	s_mov_b32 m0, s55
	s_nop 0
	global_load_lds_dwordx4 v[228:229], off
	v_lshl_add_u64 v[228:229], v[234:235], 0, s[8:9]
	s_mov_b32 m0, s56
	s_nop 0
	global_load_lds_dwordx4 v[228:229], off
	v_mov_b32_e32 v240, 0xbfb8aa3b
	v_mov_b32_e32 v241, 0xbfb8aa3b
	v_mov_b32_e32 v242, 1.0
	v_mov_b32_e32 v243, 1.0
	s_waitcnt vmcnt(8)
	s_waitcnt lgkmcnt(0)
	s_setprio 1
	s_barrier
; __device__ __forceinline__ unsigned cvt_pk_bf16(float lo, float hi) { unsigned r; asm volatile("v_cvt_pk_bf16_f32 %0, %1, %2" : "=v"(r) : "v"(lo), "v"(hi)); return r; }
; __device__ __forceinline__ float silu_mul(float g, float u) {
;     const float e = __builtin_amdgcn_exp2f(g * -1.4426950408889634f);
;     return g * __builtin_amdgcn_rcpf(1.0f + e) * u;
; }
;     __device__ __forceinline__ void pre(const Unit& u, int wr, int fr, float (&rv)[8]) const {
; #pragma unroll
;         for (int i = 0; i < 8; ++i) rv[i] = rs[u.pm * BM + wr * 64 + fr + (i >> 2) * HALF + (i & 3) * 16];
;     }
;     __device__ __forceinline__ void operator()(const f32x4 (&acc)[2][2][4][2], const Unit& u, int wr, int wc, int fr, int fq, const float (&rv)[8]) const {
;         const int row0 = u.pm * BM + wr * 64 + fr, col0 = u.pn * HALF + wc * 32 + 8 * fq;
; #pragma unroll
;         for (int ai = 0; ai < 2; ++ai)
; #pragma unroll
;             for (int m = 0; m < 4; ++m) {
;                 bf16_t* rowp = O + (size_t)(row0 + ai * HALF + m * 16) * ldc + col0;
;                 const float r = rv[ai * 4 + m];
;                 const f32x4 g0 = acc[ai][0][m][0] * r, g1 = acc[ai][0][m][1] * r, u0 = acc[ai][1][m][0] * r, u1 = acc[ai][1][m][1] * r;
;                 u32x4 w;
;                 w.x = cvt_pk_bf16(silu_mul(g0[0], u0[0]), silu_mul(g0[1], u0[1]));
;                 w.y = cvt_pk_bf16(silu_mul(g0[2], u0[2]), silu_mul(g0[3], u0[3]));
;                 w.z = cvt_pk_bf16(silu_mul(g1[0], u1[0]), silu_mul(g1[1], u1[1]));
;                 w.w = cvt_pk_bf16(silu_mul(g1[2], u1[2]), silu_mul(g1[3], u1[3]));
	v_mfma_f32_16x16x32_bf16 v[60:63], v[164:167], v[196:199], v[60:63]
	v_mfma_f32_16x16x32_bf16 v[60:63], v[168:171], v[200:203], v[60:63]
	v_pk_mul_f32 v[124:125], v[162:163], v[124:125] op_sel_hi:[0,1]
	v_pk_mul_f32 v[116:117], v[162:163], v[116:117] op_sel_hi:[0,1]
	v_pk_mul_f32 v[126:127], v[162:163], v[126:127] op_sel_hi:[0,1]
	v_pk_mul_f32 v[118:119], v[162:163], v[118:119] op_sel_hi:[0,1]
	v_mfma_f32_16x16x32_bf16 v[44:47], v[164:167], v[204:207], v[44:47]
	v_mfma_f32_16x16x32_bf16 v[44:47], v[168:171], v[208:211], v[44:47]
	v_pk_mul_f32 v[246:247], v[124:125], v[240:241]
	v_pk_mul_f32 v[248:249], v[126:127], v[240:241]
	v_exp_f32_e32 v246, v246
	v_exp_f32_e32 v247, v247
	v_mfma_f32_16x16x32_bf16 v[28:31], v[164:167], v[212:215], v[28:31]
	v_mfma_f32_16x16x32_bf16 v[28:31], v[168:171], v[216:219], v[28:31]
	v_exp_f32_e32 v248, v248
	v_exp_f32_e32 v249, v249
	v_pk_add_f32 v[246:247], v[246:247], v[242:243]
	v_pk_add_f32 v[248:249], v[248:249], v[242:243]
	v_mfma_f32_16x16x32_bf16 v[12:15], v[164:167], v[220:223], v[12:15]
	v_mfma_f32_16x16x32_bf16 v[12:15], v[168:171], v[224:227], v[12:15]
	v_rcp_f32_e32 v246, v246
	v_rcp_f32_e32 v247, v247
	v_rcp_f32_e32 v248, v248
	v_rcp_f32_e32 v249, v249
	v_mfma_f32_16x16x32_bf16 v[8:11], v[172:175], v[220:223], v[8:11]
	v_mfma_f32_16x16x32_bf16 v[8:11], v[176:179], v[224:227], v[8:11]
	v_pk_mul_f32 v[124:125], v[124:125], v[246:247]
	v_pk_mul_f32 v[126:127], v[126:127], v[248:249]
	v_pk_mul_f32 v[124:125], v[124:125], v[116:117]
	v_pk_mul_f32 v[126:127], v[126:127], v[118:119]
	v_mfma_f32_16x16x32_bf16 v[24:27], v[172:175], v[212:215], v[24:27]
	v_mfma_f32_16x16x32_bf16 v[24:27], v[176:179], v[216:219], v[24:27]
	v_pk_mul_f32 v[120:121], v[162:163], v[120:121] op_sel_hi:[0,1]
	v_pk_mul_f32 v[112:113], v[162:163], v[112:113] op_sel_hi:[0,1]
	v_pk_mul_f32 v[122:123], v[162:163], v[122:123] op_sel_hi:[0,1]
	v_pk_mul_f32 v[114:115], v[162:163], v[114:115] op_sel_hi:[0,1]
	v_mfma_f32_16x16x32_bf16 v[40:43], v[172:175], v[204:207], v[40:43]
	v_mfma_f32_16x16x32_bf16 v[40:43], v[176:179], v[208:211], v[40:43]
	v_pk_mul_f32 v[246:247], v[120:121], v[240:241]
	v_pk_mul_f32 v[248:249], v[122:123], v[240:241]
	v_exp_f32_e32 v246, v246
	v_exp_f32_e32 v247, v247
	v_mfma_f32_16x16x32_bf16 v[56:59], v[172:175], v[196:199], v[56:59]
	v_mfma_f32_16x16x32_bf16 v[56:59], v[176:179], v[200:203], v[56:59]
	v_exp_f32_e32 v248, v248
	v_exp_f32_e32 v249, v249
	v_pk_add_f32 v[246:247], v[246:247], v[242:243]
	v_pk_add_f32 v[248:249], v[248:249], v[242:243]
	v_mfma_f32_16x16x32_bf16 v[52:55], v[180:183], v[196:199], v[52:55]
	v_mfma_f32_16x16x32_bf16 v[52:55], v[184:187], v[200:203], v[52:55]
	v_rcp_f32_e32 v246, v246
	v_rcp_f32_e32 v247, v247
	v_rcp_f32_e32 v248, v248
	v_rcp_f32_e32 v249, v249
	v_mfma_f32_16x16x32_bf16 v[36:39], v[180:183], v[204:207], v[36:39]
	v_mfma_f32_16x16x32_bf16 v[36:39], v[184:187], v[208:211], v[36:39]
	v_pk_mul_f32 v[120:121], v[120:121], v[246:247]
	v_pk_mul_f32 v[122:123], v[122:123], v[248:249]
	v_pk_mul_f32 v[120:121], v[120:121], v[112:113]
	v_pk_mul_f32 v[122:123], v[122:123], v[114:115]
	v_mfma_f32_16x16x32_bf16 v[20:23], v[180:183], v[212:215], v[20:23]
	v_mfma_f32_16x16x32_bf16 v[20:23], v[184:187], v[216:219], v[20:23]
	v_cvt_pk_bf16_f32 v112, v124, v125
	v_cvt_pk_bf16_f32 v113, v126, v127
	v_cvt_pk_bf16_f32 v114, v120, v121
	v_cvt_pk_bf16_f32 v115, v122, v123
	v_mfma_f32_16x16x32_bf16 v[4:7], v[180:183], v[220:223], v[4:7]
	v_mfma_f32_16x16x32_bf16 v[4:7], v[184:187], v[224:227], v[4:7]
	v_pk_mul_f32 v[108:109], v[160:161], v[108:109] op_sel_hi:[0,1]
	v_pk_mul_f32 v[100:101], v[160:161], v[100:101] op_sel_hi:[0,1]
	v_pk_mul_f32 v[110:111], v[160:161], v[110:111] op_sel_hi:[0,1]
	v_pk_mul_f32 v[102:103], v[160:161], v[102:103] op_sel_hi:[0,1]
	v_mfma_f32_16x16x32_bf16 v[0:3], v[188:191], v[220:223], v[0:3]
	v_mfma_f32_16x16x32_bf16 v[0:3], v[192:195], v[224:227], v[0:3]
	v_pk_mul_f32 v[246:247], v[108:109], v[240:241]
	v_pk_mul_f32 v[248:249], v[110:111], v[240:241]
	v_exp_f32_e32 v246, v246
	v_exp_f32_e32 v247, v247
	v_mfma_f32_16x16x32_bf16 v[16:19], v[188:191], v[212:215], v[16:19]
	v_mfma_f32_16x16x32_bf16 v[16:19], v[192:195], v[216:219], v[16:19]
	v_exp_f32_e32 v248, v248
	v_exp_f32_e32 v249, v249
	v_pk_add_f32 v[246:247], v[246:247], v[242:243]
	v_pk_add_f32 v[248:249], v[248:249], v[242:243]
	s_setprio 2
	s_barrier
	v_mfma_f32_16x16x32_bf16 v[32:35], v[188:191], v[204:207], v[32:35]
	v_mfma_f32_16x16x32_bf16 v[32:35], v[192:195], v[208:211], v[32:35]
	v_rcp_f32_e32 v246, v246
	v_rcp_f32_e32 v247, v247
	v_rcp_f32_e32 v248, v248
	v_rcp_f32_e32 v249, v249
	v_mfma_f32_16x16x32_bf16 v[48:51], v[188:191], v[196:199], v[48:51]
	v_mfma_f32_16x16x32_bf16 v[48:51], v[192:195], v[200:203], v[48:51]
	v_pk_mul_f32 v[108:109], v[108:109], v[246:247]
	v_pk_mul_f32 v[110:111], v[110:111], v[248:249]
	v_pk_mul_f32 v[108:109], v[108:109], v[100:101]
	v_pk_mul_f32 v[110:111], v[110:111], v[102:103]
	s_setprio 0
	s_add_i32 s67, s67, 2
	s_add_u32 s44, s44, 0x100
	s_addc_u32 s45, s45, 0
	s_add_u32 s65, s65, 0x100
	s_addc_u32 s66, s66, 0
	s_and_b64 vcc, exec, s[12:13]
	s_cbranch_vccz .LBB0_703
	s_barrier
; __device__ __forceinline__ unsigned cvt_pk_bf16(float lo, float hi) { unsigned r; asm volatile("v_cvt_pk_bf16_f32 %0, %1, %2" : "=v"(r) : "v"(lo), "v"(hi)); return r; }
; __device__ __forceinline__ float silu_mul(float g, float u) {
;     const float e = __builtin_amdgcn_exp2f(g * -1.4426950408889634f);
;     return g * __builtin_amdgcn_rcpf(1.0f + e) * u;
; }
;     __device__ __forceinline__ void pre(const Unit& u, int wr, int fr, float (&rv)[8]) const {
; #pragma unroll
;         for (int i = 0; i < 8; ++i) rv[i] = rs[u.pm * BM + wr * 64 + fr + (i >> 2) * HALF + (i & 3) * 16];
;     }
;     __device__ __forceinline__ void operator()(const f32x4 (&acc)[2][2][4][2], const Unit& u, int wr, int wc, int fr, int fq, const float (&rv)[8]) const {
;         const int row0 = u.pm * BM + wr * 64 + fr, col0 = u.pn * HALF + wc * 32 + 8 * fq;
; #pragma unroll
;         for (int ai = 0; ai < 2; ++ai)
; #pragma unroll
;             for (int m = 0; m < 4; ++m) {
;                 bf16_t* rowp = O + (size_t)(row0 + ai * HALF + m * 16) * ldc + col0;
;                 const float r = rv[ai * 4 + m];
;                 const f32x4 g0 = acc[ai][0][m][0] * r, g1 = acc[ai][0][m][1] * r, u0 = acc[ai][1][m][0] * r, u1 = acc[ai][1][m][1] * r;
;                 u32x4 w;
;                 w.x = cvt_pk_bf16(silu_mul(g0[0], u0[0]), silu_mul(g0[1], u0[1]));
;                 w.y = cvt_pk_bf16(silu_mul(g0[2], u0[2]), silu_mul(g0[3], u0[3]));
;                 w.z = cvt_pk_bf16(silu_mul(g1[0], u1[0]), silu_mul(g1[1], u1[1]));
;                 w.w = cvt_pk_bf16(silu_mul(g1[2], u1[2]), silu_mul(g1[3], u1[3]));
;                 *(u32x4*)rowp = w;
.LBB0_703:
	s_waitcnt vmcnt(0)
	v_mov_b32_e32 v240, 0xbfb8aa3b
	v_mov_b32_e32 v241, 0xbfb8aa3b
	v_mov_b32_e32 v242, 1.0
	v_mov_b32_e32 v243, 1.0
	s_nop 7
	s_nop 7
	v_lshl_or_b32 v166, s64, 7, v153
	v_lshl_add_u32 v161, s42, 8, v137
	v_ashrrev_i32_e32 v167, 31, v166
	v_mov_b64_e32 v[164:165], s[14:15]
	v_mad_i64_i32 v[168:169], s[10:11], v161, s61, v[164:165]
	v_lshlrev_b64 v[166:167], 1, v[166:167]
	v_lshl_add_u64 v[168:169], v[168:169], 0, v[166:167]
	global_store_dwordx4 v[168:169], v[112:115], off
	v_pk_mul_f32 v[104:105], v[160:161], v[104:105] op_sel_hi:[0,1]
	v_pk_mul_f32 v[96:97], v[160:161], v[96:97] op_sel_hi:[0,1]
	v_pk_mul_f32 v[106:107], v[160:161], v[106:107] op_sel_hi:[0,1]
	v_pk_mul_f32 v[98:99], v[160:161], v[98:99] op_sel_hi:[0,1]
	v_pk_mul_f32 v[246:247], v[104:105], v[240:241]
	v_pk_mul_f32 v[248:249], v[106:107], v[240:241]
	v_exp_f32_e32 v246, v246
	v_exp_f32_e32 v247, v247
	v_exp_f32_e32 v248, v248
	v_exp_f32_e32 v249, v249
	v_pk_add_f32 v[246:247], v[246:247], v[242:243]
	v_pk_add_f32 v[248:249], v[248:249], v[242:243]
	v_rcp_f32_e32 v246, v246
	v_rcp_f32_e32 v247, v247
	v_rcp_f32_e32 v248, v248
	v_rcp_f32_e32 v249, v249
	v_pk_mul_f32 v[104:105], v[104:105], v[246:247]
	v_pk_mul_f32 v[106:107], v[106:107], v[248:249]
	v_pk_mul_f32 v[104:105], v[104:105], v[96:97]
	v_pk_mul_f32 v[106:107], v[106:107], v[98:99]
	v_or_b32_e32 v112, 16, v161
	v_mad_i64_i32 v[112:113], s[10:11], v112, s61, v[164:165]
	v_lshl_add_u64 v[112:113], v[112:113], 0, v[166:167]
	v_cvt_pk_bf16_f32 v96, v108, v109
	v_cvt_pk_bf16_f32 v97, v110, v111
	v_cvt_pk_bf16_f32 v98, v104, v105
	v_cvt_pk_bf16_f32 v99, v106, v107
	global_store_dwordx4 v[112:113], v[96:99], off
	v_pk_mul_f32 v[92:93], v[158:159], v[92:93] op_sel_hi:[0,1]
	v_pk_mul_f32 v[84:85], v[158:159], v[84:85] op_sel_hi:[0,1]
	v_pk_mul_f32 v[94:95], v[158:159], v[94:95] op_sel_hi:[0,1]
	v_pk_mul_f32 v[86:87], v[158:159], v[86:87] op_sel_hi:[0,1]
	v_pk_mul_f32 v[246:247], v[92:93], v[240:241]
	v_pk_mul_f32 v[248:249], v[94:95], v[240:241]
	v_exp_f32_e32 v246, v246
	v_exp_f32_e32 v247, v247
	v_exp_f32_e32 v248, v248
	v_exp_f32_e32 v249, v249
	v_pk_add_f32 v[246:247], v[246:247], v[242:243]
	v_pk_add_f32 v[248:249], v[248:249], v[242:243]
	v_rcp_f32_e32 v246, v246
	v_rcp_f32_e32 v247, v247
	v_rcp_f32_e32 v248, v248
	v_rcp_f32_e32 v249, v249
	v_pk_mul_f32 v[92:93], v[92:93], v[246:247]
	v_pk_mul_f32 v[94:95], v[94:95], v[248:249]
	v_pk_mul_f32 v[92:93], v[92:93], v[84:85]
	v_pk_mul_f32 v[94:95], v[94:95], v[86:87]
	v_or_b32_e32 v96, 32, v161
	v_mad_i64_i32 v[96:97], s[10:11], v96, s61, v[164:165]
	v_lshl_add_u64 v[96:97], v[96:97], 0, v[166:167]
	v_pk_mul_f32 v[88:89], v[158:159], v[88:89] op_sel_hi:[0,1]
	v_pk_mul_f32 v[80:81], v[158:159], v[80:81] op_sel_hi:[0,1]
	v_pk_mul_f32 v[90:91], v[158:159], v[90:91] op_sel_hi:[0,1]
	v_pk_mul_f32 v[82:83], v[158:159], v[82:83] op_sel_hi:[0,1]
	v_pk_mul_f32 v[246:247], v[88:89], v[240:241]
	v_pk_mul_f32 v[248:249], v[90:91], v[240:241]
	v_exp_f32_e32 v246, v246
	v_exp_f32_e32 v247, v247
	v_exp_f32_e32 v248, v248
	v_exp_f32_e32 v249, v249
	v_pk_add_f32 v[246:247], v[246:247], v[242:243]
	v_pk_add_f32 v[248:249], v[248:249], v[242:243]
	v_rcp_f32_e32 v246, v246
	v_rcp_f32_e32 v247, v247
	v_rcp_f32_e32 v248, v248
	v_rcp_f32_e32 v249, v249
	v_pk_mul_f32 v[88:89], v[88:89], v[246:247]
	v_pk_mul_f32 v[90:91], v[90:91], v[248:249]
	v_pk_mul_f32 v[88:89], v[88:89], v[80:81]
	v_pk_mul_f32 v[90:91], v[90:91], v[82:83]
	v_cvt_pk_bf16_f32 v80, v92, v93
	v_cvt_pk_bf16_f32 v81, v94, v95
	v_cvt_pk_bf16_f32 v82, v88, v89
	v_cvt_pk_bf16_f32 v83, v90, v91
	global_store_dwordx4 v[96:97], v[80:83], off
	v_pk_mul_f32 v[76:77], v[156:157], v[76:77] op_sel_hi:[0,1]
	v_pk_mul_f32 v[68:69], v[156:157], v[68:69] op_sel_hi:[0,1]
	v_pk_mul_f32 v[78:79], v[156:157], v[78:79] op_sel_hi:[0,1]
	v_pk_mul_f32 v[70:71], v[156:157], v[70:71] op_sel_hi:[0,1]
	v_pk_mul_f32 v[246:247], v[76:77], v[240:241]
	v_pk_mul_f32 v[248:249], v[78:79], v[240:241]
	v_exp_f32_e32 v246, v246
	v_exp_f32_e32 v247, v247
	v_exp_f32_e32 v248, v248
	v_exp_f32_e32 v249, v249
	v_pk_add_f32 v[246:247], v[246:247], v[242:243]
	v_pk_add_f32 v[248:249], v[248:249], v[242:243]
	v_rcp_f32_e32 v246, v246
	v_rcp_f32_e32 v247, v247
	v_rcp_f32_e32 v248, v248
	v_rcp_f32_e32 v249, v249
	v_pk_mul_f32 v[76:77], v[76:77], v[246:247]
	v_pk_mul_f32 v[78:79], v[78:79], v[248:249]
	v_pk_mul_f32 v[76:77], v[76:77], v[68:69]
	v_pk_mul_f32 v[78:79], v[78:79], v[70:71]
	v_or_b32_e32 v80, 48, v161
	v_mad_i64_i32 v[80:81], s[10:11], v80, s61, v[164:165]
	v_lshl_add_u64 v[80:81], v[80:81], 0, v[166:167]
	v_pk_mul_f32 v[72:73], v[156:157], v[72:73] op_sel_hi:[0,1]
	v_pk_mul_f32 v[64:65], v[156:157], v[64:65] op_sel_hi:[0,1]
	v_pk_mul_f32 v[74:75], v[156:157], v[74:75] op_sel_hi:[0,1]
	v_pk_mul_f32 v[66:67], v[156:157], v[66:67] op_sel_hi:[0,1]
	v_pk_mul_f32 v[246:247], v[72:73], v[240:241]
	v_pk_mul_f32 v[248:249], v[74:75], v[240:241]
	v_exp_f32_e32 v246, v246
	v_exp_f32_e32 v247, v247
	v_exp_f32_e32 v248, v248
	v_exp_f32_e32 v249, v249
	v_pk_add_f32 v[246:247], v[246:247], v[242:243]
	v_pk_add_f32 v[248:249], v[248:249], v[242:243]
	v_rcp_f32_e32 v246, v246
	v_rcp_f32_e32 v247, v247
	v_rcp_f32_e32 v248, v248
	v_rcp_f32_e32 v249, v249
	v_pk_mul_f32 v[72:73], v[72:73], v[246:247]
	v_pk_mul_f32 v[74:75], v[74:75], v[248:249]
	v_pk_mul_f32 v[72:73], v[72:73], v[64:65]
	v_pk_mul_f32 v[74:75], v[74:75], v[66:67]
	v_cvt_pk_bf16_f32 v64, v76, v77
	v_cvt_pk_bf16_f32 v65, v78, v79
	v_cvt_pk_bf16_f32 v66, v72, v73
	v_cvt_pk_bf16_f32 v67, v74, v75
	global_store_dwordx4 v[80:81], v[64:67], off
	v_pk_mul_f32 v[60:61], v[154:155], v[60:61] op_sel_hi:[0,1]
; __device__ __forceinline__ unsigned cvt_pk_bf16(float lo, float hi) { unsigned r; asm volatile("v_cvt_pk_bf16_f32 %0, %1, %2" : "=v"(r) : "v"(lo), "v"(hi)); return r; }
; __device__ __forceinline__ float silu_mul(float g, float u) {
;     const float e = __builtin_amdgcn_exp2f(g * -1.4426950408889634f);
;     return g * __builtin_amdgcn_rcpf(1.0f + e) * u;
; }
;     __device__ __forceinline__ void pre(const Unit& u, int wr, int fr, float (&rv)[8]) const {
; #pragma unroll
;         for (int i = 0; i < 8; ++i) rv[i] = rs[u.pm * BM + wr * 64 + fr + (i >> 2) * HALF + (i & 3) * 16];
;     }
;     __device__ __forceinline__ void operator()(const f32x4 (&acc)[2][2][4][2], const Unit& u, int wr, int wc, int fr, int fq, const float (&rv)[8]) const {
;         const int row0 = u.pm * BM + wr * 64 + fr, col0 = u.pn * HALF + wc * 32 + 8 * fq;
; #pragma unroll
;         for (int ai = 0; ai < 2; ++ai)
; #pragma unroll
;             for (int m = 0; m < 4; ++m) {
;                 bf16_t* rowp = O + (size_t)(row0 + ai * HALF + m * 16) * ldc + col0;
;                 const float r = rv[ai * 4 + m];
;                 const f32x4 g0 = acc[ai][0][m][0] * r, g1 = acc[ai][0][m][1] * r, u0 = acc[ai][1][m][0] * r, u1 = acc[ai][1][m][1] * r;
;                 u32x4 w;
;                 w.x = cvt_pk_bf16(silu_mul(g0[0], u0[0]), silu_mul(g0[1], u0[1]));
;                 w.y = cvt_pk_bf16(silu_mul(g0[2], u0[2]), silu_mul(g0[3], u0[3]));
;                 w.z = cvt_pk_bf16(silu_mul(g1[0], u1[0]), silu_mul(g1[1], u1[1]));
;                 w.w = cvt_pk_bf16(silu_mul(g1[2], u1[2]), silu_mul(g1[3], u1[3]));
;                 *(u32x4*)rowp = w;
	v_pk_mul_f32 v[52:53], v[154:155], v[52:53] op_sel_hi:[0,1]
	v_pk_mul_f32 v[62:63], v[154:155], v[62:63] op_sel_hi:[0,1]
	v_pk_mul_f32 v[54:55], v[154:155], v[54:55] op_sel_hi:[0,1]
	v_pk_mul_f32 v[246:247], v[60:61], v[240:241]
	v_pk_mul_f32 v[248:249], v[62:63], v[240:241]
	v_exp_f32_e32 v246, v246
	v_exp_f32_e32 v247, v247
	v_exp_f32_e32 v248, v248
	v_exp_f32_e32 v249, v249
	v_pk_add_f32 v[246:247], v[246:247], v[242:243]
	v_pk_add_f32 v[248:249], v[248:249], v[242:243]
	v_rcp_f32_e32 v246, v246
	v_rcp_f32_e32 v247, v247
	v_rcp_f32_e32 v248, v248
	v_rcp_f32_e32 v249, v249
	v_pk_mul_f32 v[60:61], v[60:61], v[246:247]
	v_pk_mul_f32 v[62:63], v[62:63], v[248:249]
	v_pk_mul_f32 v[60:61], v[60:61], v[52:53]
	v_pk_mul_f32 v[62:63], v[62:63], v[54:55]
	v_add_u32_e32 v64, 0x80, v161
	v_mad_i64_i32 v[64:65], s[10:11], v64, s61, v[164:165]
	v_lshl_add_u64 v[64:65], v[64:65], 0, v[166:167]
	v_pk_mul_f32 v[56:57], v[154:155], v[56:57] op_sel_hi:[0,1]
	v_pk_mul_f32 v[48:49], v[154:155], v[48:49] op_sel_hi:[0,1]
	v_pk_mul_f32 v[58:59], v[154:155], v[58:59] op_sel_hi:[0,1]
	v_pk_mul_f32 v[50:51], v[154:155], v[50:51] op_sel_hi:[0,1]
	v_pk_mul_f32 v[246:247], v[56:57], v[240:241]
	v_pk_mul_f32 v[248:249], v[58:59], v[240:241]
	v_exp_f32_e32 v246, v246
	v_exp_f32_e32 v247, v247
	v_exp_f32_e32 v248, v248
	v_exp_f32_e32 v249, v249
	v_pk_add_f32 v[246:247], v[246:247], v[242:243]
	v_pk_add_f32 v[248:249], v[248:249], v[242:243]
	v_rcp_f32_e32 v246, v246
	v_rcp_f32_e32 v247, v247
	v_rcp_f32_e32 v248, v248
	v_rcp_f32_e32 v249, v249
	v_pk_mul_f32 v[56:57], v[56:57], v[246:247]
	v_pk_mul_f32 v[58:59], v[58:59], v[248:249]
	v_pk_mul_f32 v[56:57], v[56:57], v[48:49]
	v_pk_mul_f32 v[58:59], v[58:59], v[50:51]
	v_cvt_pk_bf16_f32 v48, v60, v61
	v_cvt_pk_bf16_f32 v49, v62, v63
	v_cvt_pk_bf16_f32 v50, v56, v57
	v_cvt_pk_bf16_f32 v51, v58, v59
	global_store_dwordx4 v[64:65], v[48:51], off
	v_pk_mul_f32 v[44:45], v[152:153], v[44:45] op_sel_hi:[0,1]
	v_pk_mul_f32 v[36:37], v[152:153], v[36:37] op_sel_hi:[0,1]
	v_pk_mul_f32 v[46:47], v[152:153], v[46:47] op_sel_hi:[0,1]
	v_pk_mul_f32 v[38:39], v[152:153], v[38:39] op_sel_hi:[0,1]
	v_pk_mul_f32 v[246:247], v[44:45], v[240:241]
	v_pk_mul_f32 v[248:249], v[46:47], v[240:241]
	v_exp_f32_e32 v246, v246
	v_exp_f32_e32 v247, v247
	v_exp_f32_e32 v248, v248
	v_exp_f32_e32 v249, v249
	v_pk_add_f32 v[246:247], v[246:247], v[242:243]
	v_pk_add_f32 v[248:249], v[248:249], v[242:243]
	v_rcp_f32_e32 v246, v246
	v_rcp_f32_e32 v247, v247
	v_rcp_f32_e32 v248, v248
	v_rcp_f32_e32 v249, v249
	v_pk_mul_f32 v[44:45], v[44:45], v[246:247]
	v_pk_mul_f32 v[46:47], v[46:47], v[248:249]
	v_pk_mul_f32 v[44:45], v[44:45], v[36:37]
	v_pk_mul_f32 v[46:47], v[46:47], v[38:39]
	v_add_u32_e32 v48, 0x90, v161
	v_mad_i64_i32 v[48:49], s[10:11], v48, s61, v[164:165]
	v_lshl_add_u64 v[48:49], v[48:49], 0, v[166:167]
	v_pk_mul_f32 v[40:41], v[152:153], v[40:41] op_sel_hi:[0,1]
	v_pk_mul_f32 v[32:33], v[152:153], v[32:33] op_sel_hi:[0,1]
	v_pk_mul_f32 v[42:43], v[152:153], v[42:43] op_sel_hi:[0,1]
	v_pk_mul_f32 v[34:35], v[152:153], v[34:35] op_sel_hi:[0,1]
	v_pk_mul_f32 v[246:247], v[40:41], v[240:241]
	v_pk_mul_f32 v[248:249], v[42:43], v[240:241]
	v_exp_f32_e32 v246, v246
	v_exp_f32_e32 v247, v247
	v_exp_f32_e32 v248, v248
	v_exp_f32_e32 v249, v249
	v_pk_add_f32 v[246:247], v[246:247], v[242:243]
	v_pk_add_f32 v[248:249], v[248:249], v[242:243]
	v_rcp_f32_e32 v246, v246
	v_rcp_f32_e32 v247, v247
	v_rcp_f32_e32 v248, v248
	v_rcp_f32_e32 v249, v249
	v_pk_mul_f32 v[40:41], v[40:41], v[246:247]
	v_pk_mul_f32 v[42:43], v[42:43], v[248:249]
	v_pk_mul_f32 v[40:41], v[40:41], v[32:33]
	v_pk_mul_f32 v[42:43], v[42:43], v[34:35]
	v_cvt_pk_bf16_f32 v32, v44, v45
	v_cvt_pk_bf16_f32 v33, v46, v47
	v_cvt_pk_bf16_f32 v34, v40, v41
	v_cvt_pk_bf16_f32 v35, v42, v43
	global_store_dwordx4 v[48:49], v[32:35], off
	v_pk_mul_f32 v[28:29], v[146:147], v[28:29] op_sel_hi:[0,1]
	v_pk_mul_f32 v[20:21], v[146:147], v[20:21] op_sel_hi:[0,1]
	v_pk_mul_f32 v[30:31], v[146:147], v[30:31] op_sel_hi:[0,1]
	v_pk_mul_f32 v[22:23], v[146:147], v[22:23] op_sel_hi:[0,1]
	v_pk_mul_f32 v[246:247], v[28:29], v[240:241]
	v_pk_mul_f32 v[248:249], v[30:31], v[240:241]
; #define PG8_BAR __builtin_amdgcn_s_barrier()
; __device__ __forceinline__ float silu_mul(float g, float u) {
;     const float e = __builtin_amdgcn_exp2f(g * -1.4426950408889634f);
;     return g * __builtin_amdgcn_rcpf(1.0f + e) * u;
; }
;     __device__ __forceinline__ void pre(const Unit& u, int wr, int fr, float (&rv)[8]) const {
; #pragma unroll
;         for (int i = 0; i < 8; ++i) rv[i] = rs[u.pm * BM + wr * 64 + fr + (i >> 2) * HALF + (i & 3) * 16];
;     }
;     __device__ __forceinline__ void operator()(const f32x4 (&acc)[2][2][4][2], const Unit& u, int wr, int wc, int fr, int fq, const float (&rv)[8]) const {
;         const int row0 = u.pm * BM + wr * 64 + fr, col0 = u.pn * HALF + wc * 32 + 8 * fq;
; #pragma unroll
;         for (int ai = 0; ai < 2; ++ai)
; #pragma unroll
;             for (int m = 0; m < 4; ++m) {
;                 bf16_t* rowp = O + (size_t)(row0 + ai * HALF + m * 16) * ldc + col0;
;                 const float r = rv[ai * 4 + m];
;                 const f32x4 g0 = acc[ai][0][m][0] * r, g1 = acc[ai][0][m][1] * r, u0 = acc[ai][1][m][0] * r, u1 = acc[ai][1][m][1] * r;
;                 u32x4 w;
;                 w.x = cvt_pk_bf16(silu_mul(g0[0], u0[0]), silu_mul(g0[1], u0[1]));
;                 w.y = cvt_pk_bf16(silu_mul(g0[2], u0[2]), silu_mul(g0[3], u0[3]));
;                 w.z = cvt_pk_bf16(silu_mul(g1[0], u1[0]), silu_mul(g1[1], u1[1]));
;                 w.w = cvt_pk_bf16(silu_mul(g1[2], u1[2]), silu_mul(g1[3], u1[3]));
;                 *(u32x4*)rowp = w;
; template <class Epi, class Sched, bool ALIGN_EPI = false, bool SP2 = false>
; __device__ __forceinline__ void gemm_phase(PG8_LAS unsigned char* lds, const Gemm g, const Sched& S, const Epi& E) {
;     ...
;         if constexpr (!Epi::AFTER_DRAIN) { E(acc, cur, wr, wc, fr, fq, epre); S.done(cur); }
;         if (!has_next) break;
; #pragma unroll
;         for (int a = 0; a < 2; ++a)
; #pragma unroll
;             for (int b = 0; b < 2; ++b)
; #pragma unroll
;                 for (int m = 0; m < 4; ++m)
; #pragma unroll
;                     for (int n = 0; n < 2; ++n) acc[a][b][m][n] = (f32x4){0.f, 0.f, 0.f, 0.f};
;         cur = nxt; cA = nA; cB = nB; ++ui;
;         E.pre(cur, wr, fr, epre);
;         if constexpr (ALIGN_EPI) { if (wr == 1) PG8_BAR; }
	v_exp_f32_e32 v246, v246
	v_exp_f32_e32 v247, v247
	v_exp_f32_e32 v248, v248
	v_exp_f32_e32 v249, v249
	v_pk_add_f32 v[246:247], v[246:247], v[242:243]
	v_pk_add_f32 v[248:249], v[248:249], v[242:243]
	v_rcp_f32_e32 v246, v246
	v_rcp_f32_e32 v247, v247
	v_rcp_f32_e32 v248, v248
	v_rcp_f32_e32 v249, v249
	v_pk_mul_f32 v[28:29], v[28:29], v[246:247]
	v_pk_mul_f32 v[30:31], v[30:31], v[248:249]
	v_pk_mul_f32 v[28:29], v[28:29], v[20:21]
	v_pk_mul_f32 v[30:31], v[30:31], v[22:23]
	v_add_u32_e32 v32, 0xa0, v161
	v_mad_i64_i32 v[32:33], s[10:11], v32, s61, v[164:165]
	v_lshl_add_u64 v[32:33], v[32:33], 0, v[166:167]
	v_pk_mul_f32 v[24:25], v[146:147], v[24:25] op_sel_hi:[0,1]
	v_pk_mul_f32 v[16:17], v[146:147], v[16:17] op_sel_hi:[0,1]
	v_pk_mul_f32 v[26:27], v[146:147], v[26:27] op_sel_hi:[0,1]
	v_pk_mul_f32 v[18:19], v[146:147], v[18:19] op_sel_hi:[0,1]
	v_pk_mul_f32 v[246:247], v[24:25], v[240:241]
	v_pk_mul_f32 v[248:249], v[26:27], v[240:241]
	v_exp_f32_e32 v246, v246
	v_exp_f32_e32 v247, v247
	v_exp_f32_e32 v248, v248
	v_exp_f32_e32 v249, v249
	v_pk_add_f32 v[246:247], v[246:247], v[242:243]
	v_pk_add_f32 v[248:249], v[248:249], v[242:243]
	v_rcp_f32_e32 v246, v246
	v_rcp_f32_e32 v247, v247
	v_rcp_f32_e32 v248, v248
	v_rcp_f32_e32 v249, v249
	v_pk_mul_f32 v[24:25], v[24:25], v[246:247]
	v_pk_mul_f32 v[26:27], v[26:27], v[248:249]
	v_pk_mul_f32 v[24:25], v[24:25], v[16:17]
	v_pk_mul_f32 v[26:27], v[26:27], v[18:19]
	v_cvt_pk_bf16_f32 v16, v28, v29
	v_cvt_pk_bf16_f32 v17, v30, v31
	v_cvt_pk_bf16_f32 v18, v24, v25
	v_cvt_pk_bf16_f32 v19, v26, v27
	global_store_dwordx4 v[32:33], v[16:19], off
	v_pk_mul_f32 v[12:13], v[136:137], v[12:13] op_sel_hi:[0,1]
	v_pk_mul_f32 v[4:5], v[136:137], v[4:5] op_sel_hi:[0,1]
	v_pk_mul_f32 v[14:15], v[136:137], v[14:15] op_sel_hi:[0,1]
	v_pk_mul_f32 v[6:7], v[136:137], v[6:7] op_sel_hi:[0,1]
	v_pk_mul_f32 v[246:247], v[12:13], v[240:241]
	v_pk_mul_f32 v[248:249], v[14:15], v[240:241]
	v_exp_f32_e32 v246, v246
	v_exp_f32_e32 v247, v247
	v_exp_f32_e32 v248, v248
	v_exp_f32_e32 v249, v249
	v_pk_add_f32 v[246:247], v[246:247], v[242:243]
	v_pk_add_f32 v[248:249], v[248:249], v[242:243]
	v_rcp_f32_e32 v246, v246
	v_rcp_f32_e32 v247, v247
	v_rcp_f32_e32 v248, v248
	v_rcp_f32_e32 v249, v249
	v_pk_mul_f32 v[12:13], v[12:13], v[246:247]
	v_pk_mul_f32 v[14:15], v[14:15], v[248:249]
	v_pk_mul_f32 v[12:13], v[12:13], v[4:5]
	v_pk_mul_f32 v[14:15], v[14:15], v[6:7]
	v_add_u32_e32 v16, 0xb0, v161
	v_mad_i64_i32 v[16:17], s[10:11], v16, s61, v[164:165]
	v_lshl_add_u64 v[16:17], v[16:17], 0, v[166:167]
	s_andn2_b64 vcc, exec, s[0:1]
	s_mov_b64 s[0:1], -1
	v_pk_mul_f32 v[8:9], v[136:137], v[8:9] op_sel_hi:[0,1]
	v_pk_mul_f32 v[0:1], v[136:137], v[0:1] op_sel_hi:[0,1]
	v_pk_mul_f32 v[10:11], v[136:137], v[10:11] op_sel_hi:[0,1]
	v_pk_mul_f32 v[2:3], v[136:137], v[2:3] op_sel_hi:[0,1]
	v_pk_mul_f32 v[246:247], v[8:9], v[240:241]
	v_pk_mul_f32 v[248:249], v[10:11], v[240:241]
	v_exp_f32_e32 v246, v246
	v_exp_f32_e32 v247, v247
	v_exp_f32_e32 v248, v248
	v_exp_f32_e32 v249, v249
	v_pk_add_f32 v[246:247], v[246:247], v[242:243]
	v_pk_add_f32 v[248:249], v[248:249], v[242:243]
	v_rcp_f32_e32 v246, v246
	v_rcp_f32_e32 v247, v247
	v_rcp_f32_e32 v248, v248
	v_rcp_f32_e32 v249, v249
	v_pk_mul_f32 v[8:9], v[8:9], v[246:247]
	v_pk_mul_f32 v[10:11], v[10:11], v[248:249]
	v_pk_mul_f32 v[8:9], v[8:9], v[0:1]
	v_pk_mul_f32 v[10:11], v[10:11], v[2:3]
	v_cvt_pk_bf16_f32 v0, v12, v13
	v_cvt_pk_bf16_f32 v1, v14, v15
	v_cvt_pk_bf16_f32 v2, v8, v9
	v_cvt_pk_bf16_f32 v3, v10, v11
	global_store_dwordx4 v[16:17], v[0:3], off
	s_cbranch_vccnz .LBB0_696
	s_nop 0
	v_lshl_add_u32 v0, s36, 8, v137
	v_ashrrev_i32_e32 v1, 31, v0
	v_lshl_add_u64 v[0:1], v[0:1], 2, s[16:17]
	global_load_dword v162, v[0:1], off
	global_load_dword v160, v[0:1], off offset:64
	global_load_dword v158, v[0:1], off offset:128
	global_load_dword v156, v[0:1], off offset:192
	global_load_dword v154, v[0:1], off offset:512
	global_load_dword v152, v[0:1], off offset:576
	global_load_dword v146, v[0:1], off offset:640
	global_load_dword v136, v[0:1], off offset:704
	s_andn2_b64 vcc, exec, s[4:5]
	s_cbranch_vccnz .LBB0_695
	s_barrier
	s_branch .LBB0_695
